# GEMM K-loops: 32 MFMAs per compute segment reordered: accumulator pairs adjacent (k0k1 / k1k0 alternating) and consecutive pairs share srcA or srcB; mid setprio pair removed
# speedup vs baseline: 1.0162x; 1.0061x over previous
.LBB0_252:
	s_add_u32 s12, s54, 0xfff00080
	s_addc_u32 s13, s55, -1
	s_add_i32 s95, 0, 0x10000
	s_cmp_eq_u32 s94, 60
	s_cselect_b32 s65, s47, s13
	s_cselect_b32 s64, s66, s12
	v_add_u32_e32 v142, s95, v144
	s_cselect_b32 s63, s45, s61
	s_cselect_b32 s62, vcc_lo, vcc_hi
	s_add_i32 s56, 0, 0x14000
	ds_read_b128 v[148:151], v142
	ds_read_b128 v[152:155], v142 offset:1024
	ds_read_b128 v[156:159], v142 offset:2048
	ds_read_b128 v[160:163], v142 offset:3072
	v_add_u32_e32 v142, s56, v144
	ds_read_b128 v[164:167], v142
	ds_read_b128 v[168:171], v142 offset:1024
	ds_read_b128 v[172:175], v142 offset:2048
	ds_read_b128 v[176:179], v142 offset:3072
	v_lshl_add_u64 v[142:143], s[54:55], 0, v[136:137]
	s_add_i32 m0, s53, 0xc000
	ds_read_b128 v[180:183], v146
	ds_read_b128 v[184:187], v146 offset:1024
	ds_read_b128 v[210:213], v146 offset:2048
	ds_read_b128 v[214:217], v146 offset:3072
	ds_read_b128 v[218:221], v146 offset:4096
	ds_read_b128 v[222:225], v146 offset:5120
	ds_read_b128 v[226:229], v146 offset:6144
	ds_read_b128 v[230:233], v146 offset:7168
	global_load_lds_dwordx4 v[142:143], off
	v_lshl_add_u64 v[142:143], s[54:55], 0, v[138:139]
	s_add_i32 m0, s53, 0xe000
	s_nop 0
	global_load_lds_dwordx4 v[142:143], off
	s_waitcnt vmcnt(8)
	s_waitcnt lgkmcnt(0)
	s_barrier
	s_setprio 1
	s_waitcnt lgkmcnt(0)
	v_mfma_f32_16x16x32_bf16 v[126:129], v[148:151], v[180:183], v[126:129]
	v_mfma_f32_16x16x32_bf16 v[126:129], v[152:155], v[184:187], v[126:129]
	v_mfma_f32_16x16x32_bf16 v[114:117], v[152:155], v[214:217], v[114:117]
	v_mfma_f32_16x16x32_bf16 v[114:117], v[148:151], v[210:213], v[114:117]
	v_mfma_f32_16x16x32_bf16 v[98:101], v[148:151], v[218:221], v[98:101]
	v_mfma_f32_16x16x32_bf16 v[98:101], v[152:155], v[222:225], v[98:101]
	v_mfma_f32_16x16x32_bf16 v[82:85], v[152:155], v[230:233], v[82:85]
	v_mfma_f32_16x16x32_bf16 v[82:85], v[148:151], v[226:229], v[82:85]
	v_mfma_f32_16x16x32_bf16 v[74:77], v[156:159], v[226:229], v[74:77]
	v_mfma_f32_16x16x32_bf16 v[74:77], v[160:163], v[230:233], v[74:77]
	v_mfma_f32_16x16x32_bf16 v[90:93], v[160:163], v[222:225], v[90:93]
	v_mfma_f32_16x16x32_bf16 v[90:93], v[156:159], v[218:221], v[90:93]
	v_mfma_f32_16x16x32_bf16 v[106:109], v[156:159], v[210:213], v[106:109]
	v_mfma_f32_16x16x32_bf16 v[106:109], v[160:163], v[214:217], v[106:109]
	v_mfma_f32_16x16x32_bf16 v[122:125], v[160:163], v[184:187], v[122:125]
	v_mfma_f32_16x16x32_bf16 v[122:125], v[156:159], v[180:183], v[122:125]
	v_mfma_f32_16x16x32_bf16 v[110:113], v[172:175], v[180:183], v[110:113]
	v_mfma_f32_16x16x32_bf16 v[110:113], v[176:179], v[184:187], v[110:113]
	v_mfma_f32_16x16x32_bf16 v[94:97], v[176:179], v[214:217], v[94:97]
	v_mfma_f32_16x16x32_bf16 v[94:97], v[172:175], v[210:213], v[94:97]
	v_mfma_f32_16x16x32_bf16 v[78:81], v[172:175], v[218:221], v[78:81]
	v_mfma_f32_16x16x32_bf16 v[78:81], v[176:179], v[222:225], v[78:81]
	v_mfma_f32_16x16x32_bf16 v[66:69], v[176:179], v[230:233], v[66:69]
	v_mfma_f32_16x16x32_bf16 v[66:69], v[172:175], v[226:229], v[66:69]
	v_mfma_f32_16x16x32_bf16 v[70:73], v[164:167], v[226:229], v[70:73]
	v_mfma_f32_16x16x32_bf16 v[70:73], v[168:171], v[230:233], v[70:73]
	v_mfma_f32_16x16x32_bf16 v[86:89], v[168:171], v[222:225], v[86:89]
	v_mfma_f32_16x16x32_bf16 v[86:89], v[164:167], v[218:221], v[86:89]
	v_mfma_f32_16x16x32_bf16 v[102:105], v[164:167], v[210:213], v[102:105]
	v_mfma_f32_16x16x32_bf16 v[102:105], v[168:171], v[214:217], v[102:105]
	v_mfma_f32_16x16x32_bf16 v[118:121], v[168:171], v[184:187], v[118:121]
	v_mfma_f32_16x16x32_bf16 v[118:121], v[164:167], v[180:183], v[118:121]
	s_setprio 0
	s_barrier
	s_add_i32 s12, s95, s82
	v_lshl_add_u64 v[142:143], s[62:63], 0, v[190:191]
	s_mov_b32 m0, s12
	ds_read_b128 v[180:183], v146 offset:16384
	ds_read_b128 v[184:187], v146 offset:17408
	ds_read_b128 v[210:213], v146 offset:18432
	ds_read_b128 v[214:217], v146 offset:19456
	ds_read_b128 v[218:221], v146 offset:20480
	ds_read_b128 v[222:225], v146 offset:21504
	ds_read_b128 v[226:229], v146 offset:22528
	ds_read_b128 v[230:233], v146 offset:23552
	global_load_lds_dwordx4 v[142:143], off
	s_add_i32 m0, s12, 0x2000
	s_add_u32 s12, s62, 0x100000
	v_lshl_add_u64 v[188:189], s[62:63], 0, v[134:135]
	s_addc_u32 s13, s63, 0
	s_add_i32 s56, s56, s82
	global_load_lds_dwordx4 v[188:189], off
	v_lshl_add_u64 v[234:235], s[12:13], 0, v[190:191]
	s_mov_b32 m0, s56
	v_lshl_add_u64 v[244:245], s[64:65], 0, v[132:133]
	global_load_lds_dwordx4 v[234:235], off
	v_lshl_add_u64 v[234:235], s[12:13], 0, v[134:135]
	s_add_i32 m0, s56, 0x2000
	s_nop 0
	global_load_lds_dwordx4 v[234:235], off
	v_lshl_add_u64 v[234:235], s[64:65], 0, v[130:131]
	s_mov_b32 m0, s53
	s_nop 0
	global_load_lds_dwordx4 v[234:235], off
	s_mov_b32 m0, s84
	s_nop 0
	global_load_lds_dwordx4 v[244:245], off
	s_waitcnt vmcnt(8)
	s_waitcnt lgkmcnt(0)
	s_barrier
	s_setprio 1
	s_waitcnt lgkmcnt(0)
	v_mfma_f32_16x16x32_bf16 v[62:65], v[148:151], v[180:183], v[62:65]
	v_mfma_f32_16x16x32_bf16 v[62:65], v[152:155], v[184:187], v[62:65]
	v_mfma_f32_16x16x32_bf16 v[50:53], v[152:155], v[214:217], v[50:53]
	v_mfma_f32_16x16x32_bf16 v[50:53], v[148:151], v[210:213], v[50:53]
	v_mfma_f32_16x16x32_bf16 v[34:37], v[148:151], v[218:221], v[34:37]
	v_mfma_f32_16x16x32_bf16 v[34:37], v[152:155], v[222:225], v[34:37]
	v_mfma_f32_16x16x32_bf16 v[18:21], v[152:155], v[230:233], v[18:21]
	v_mfma_f32_16x16x32_bf16 v[18:21], v[148:151], v[226:229], v[18:21]
	v_mfma_f32_16x16x32_bf16 v[10:13], v[156:159], v[226:229], v[10:13]
	v_mfma_f32_16x16x32_bf16 v[10:13], v[160:163], v[230:233], v[10:13]
	v_mfma_f32_16x16x32_bf16 v[26:29], v[160:163], v[222:225], v[26:29]
	v_mfma_f32_16x16x32_bf16 v[26:29], v[156:159], v[218:221], v[26:29]
	v_mfma_f32_16x16x32_bf16 v[42:45], v[156:159], v[210:213], v[42:45]
	v_mfma_f32_16x16x32_bf16 v[42:45], v[160:163], v[214:217], v[42:45]
	v_mfma_f32_16x16x32_bf16 v[58:61], v[160:163], v[184:187], v[58:61]
	v_mfma_f32_16x16x32_bf16 v[58:61], v[156:159], v[180:183], v[58:61]
	v_mfma_f32_16x16x32_bf16 v[46:49], v[172:175], v[180:183], v[46:49]
	v_mfma_f32_16x16x32_bf16 v[46:49], v[176:179], v[184:187], v[46:49]
	v_mfma_f32_16x16x32_bf16 v[30:33], v[176:179], v[214:217], v[30:33]
	v_mfma_f32_16x16x32_bf16 v[30:33], v[172:175], v[210:213], v[30:33]
	v_mfma_f32_16x16x32_bf16 v[14:17], v[172:175], v[218:221], v[14:17]
	v_mfma_f32_16x16x32_bf16 v[14:17], v[176:179], v[222:225], v[14:17]
	v_mfma_f32_16x16x32_bf16 v[2:5], v[176:179], v[230:233], v[2:5]
	v_mfma_f32_16x16x32_bf16 v[2:5], v[172:175], v[226:229], v[2:5]
	v_mfma_f32_16x16x32_bf16 v[6:9], v[164:167], v[226:229], v[6:9]
	v_mfma_f32_16x16x32_bf16 v[6:9], v[168:171], v[230:233], v[6:9]
	v_mfma_f32_16x16x32_bf16 v[22:25], v[168:171], v[222:225], v[22:25]
	v_mfma_f32_16x16x32_bf16 v[22:25], v[164:167], v[218:221], v[22:25]
	v_mfma_f32_16x16x32_bf16 v[38:41], v[164:167], v[210:213], v[38:41]
	v_mfma_f32_16x16x32_bf16 v[38:41], v[168:171], v[214:217], v[38:41]
	v_mfma_f32_16x16x32_bf16 v[54:57], v[168:171], v[184:187], v[54:57]
	v_mfma_f32_16x16x32_bf16 v[54:57], v[164:167], v[180:183], v[54:57]
	s_setprio 0
	s_barrier
	s_add_i32 s56, 0, 0x18000
	v_add_u32_e32 v147, s56, v144
	s_add_i32 s95, 0, 0x1c000
	ds_read_b128 v[148:151], v147
	ds_read_b128 v[152:155], v147 offset:1024
	ds_read_b128 v[156:159], v147 offset:2048
	ds_read_b128 v[160:163], v147 offset:3072
	v_add_u32_e32 v147, s95, v144
	ds_read_b128 v[164:167], v147
	ds_read_b128 v[168:171], v147 offset:1024
	ds_read_b128 v[172:175], v147 offset:2048
	ds_read_b128 v[176:179], v147 offset:3072
	s_add_u32 s12, s64, 0x100000
	s_addc_u32 s13, s65, 0
	s_mov_b32 m0, s85
	v_lshl_add_u64 v[246:247], s[12:13], 0, v[130:131]
	ds_read_b128 v[180:183], v146 offset:32768
	ds_read_b128 v[184:187], v146 offset:33792
	ds_read_b128 v[210:213], v146 offset:34816
	ds_read_b128 v[214:217], v146 offset:35840
	ds_read_b128 v[218:221], v146 offset:36864
	ds_read_b128 v[222:225], v146 offset:37888
	ds_read_b128 v[226:229], v146 offset:38912
	ds_read_b128 v[230:233], v146 offset:39936
	global_load_lds_dwordx4 v[246:247], off
	v_lshl_add_u64 v[246:247], s[12:13], 0, v[132:133]
	s_mov_b32 m0, s86
	s_nop 0
	global_load_lds_dwordx4 v[246:247], off
	s_waitcnt vmcnt(8)
	s_waitcnt lgkmcnt(0)
	s_barrier
	s_setprio 1
	s_waitcnt lgkmcnt(0)
	v_mfma_f32_16x16x32_bf16 v[126:129], v[148:151], v[180:183], v[126:129]
	v_mfma_f32_16x16x32_bf16 v[126:129], v[152:155], v[184:187], v[126:129]
	v_mfma_f32_16x16x32_bf16 v[114:117], v[152:155], v[214:217], v[114:117]
	v_mfma_f32_16x16x32_bf16 v[114:117], v[148:151], v[210:213], v[114:117]
	v_mfma_f32_16x16x32_bf16 v[98:101], v[148:151], v[218:221], v[98:101]
	v_mfma_f32_16x16x32_bf16 v[98:101], v[152:155], v[222:225], v[98:101]
	v_mfma_f32_16x16x32_bf16 v[82:85], v[152:155], v[230:233], v[82:85]
	v_mfma_f32_16x16x32_bf16 v[82:85], v[148:151], v[226:229], v[82:85]
	v_mfma_f32_16x16x32_bf16 v[74:77], v[156:159], v[226:229], v[74:77]
	v_mfma_f32_16x16x32_bf16 v[74:77], v[160:163], v[230:233], v[74:77]
	v_mfma_f32_16x16x32_bf16 v[90:93], v[160:163], v[222:225], v[90:93]
	v_mfma_f32_16x16x32_bf16 v[90:93], v[156:159], v[218:221], v[90:93]
	v_mfma_f32_16x16x32_bf16 v[106:109], v[156:159], v[210:213], v[106:109]
	v_mfma_f32_16x16x32_bf16 v[106:109], v[160:163], v[214:217], v[106:109]
	v_mfma_f32_16x16x32_bf16 v[122:125], v[160:163], v[184:187], v[122:125]
	v_mfma_f32_16x16x32_bf16 v[122:125], v[156:159], v[180:183], v[122:125]
	v_mfma_f32_16x16x32_bf16 v[110:113], v[172:175], v[180:183], v[110:113]
	v_mfma_f32_16x16x32_bf16 v[110:113], v[176:179], v[184:187], v[110:113]
	v_mfma_f32_16x16x32_bf16 v[94:97], v[176:179], v[214:217], v[94:97]
	v_mfma_f32_16x16x32_bf16 v[94:97], v[172:175], v[210:213], v[94:97]
	v_mfma_f32_16x16x32_bf16 v[78:81], v[172:175], v[218:221], v[78:81]
	v_mfma_f32_16x16x32_bf16 v[78:81], v[176:179], v[222:225], v[78:81]
	v_mfma_f32_16x16x32_bf16 v[66:69], v[176:179], v[230:233], v[66:69]
	v_mfma_f32_16x16x32_bf16 v[66:69], v[172:175], v[226:229], v[66:69]
	v_mfma_f32_16x16x32_bf16 v[70:73], v[164:167], v[226:229], v[70:73]
	v_mfma_f32_16x16x32_bf16 v[70:73], v[168:171], v[230:233], v[70:73]
	v_mfma_f32_16x16x32_bf16 v[86:89], v[168:171], v[222:225], v[86:89]
	v_mfma_f32_16x16x32_bf16 v[86:89], v[164:167], v[218:221], v[86:89]
	v_mfma_f32_16x16x32_bf16 v[102:105], v[164:167], v[210:213], v[102:105]
	v_mfma_f32_16x16x32_bf16 v[102:105], v[168:171], v[214:217], v[102:105]
	v_mfma_f32_16x16x32_bf16 v[118:121], v[168:171], v[184:187], v[118:121]
	v_mfma_f32_16x16x32_bf16 v[118:121], v[164:167], v[180:183], v[118:121]
	s_setprio 0
	s_barrier
	s_add_i32 s12, s56, s82
	v_lshl_add_u64 v[142:143], v[142:143], 0, s[34:35]
	s_mov_b32 m0, s12
	ds_read_b128 v[180:183], v146 offset:49152
	ds_read_b128 v[184:187], v146 offset:50176
	ds_read_b128 v[210:213], v146 offset:51200
	ds_read_b128 v[214:217], v146 offset:52224
	ds_read_b128 v[218:221], v146 offset:53248
	ds_read_b128 v[222:225], v146 offset:54272
	ds_read_b128 v[226:229], v146 offset:55296
	ds_read_b128 v[230:233], v146 offset:56320
	global_load_lds_dwordx4 v[142:143], off
	s_add_i32 m0, s12, 0x2000
	s_add_u32 s12, s62, 0x100080
	v_lshl_add_u64 v[142:143], v[188:189], 0, s[34:35]
	s_addc_u32 s13, s63, 0
	s_add_i32 s56, s95, s82
	global_load_lds_dwordx4 v[142:143], off
	v_lshl_add_u64 v[142:143], s[12:13], 0, v[190:191]
	s_mov_b32 m0, s56
	s_nop 0
	global_load_lds_dwordx4 v[142:143], off
	v_lshl_add_u64 v[142:143], s[12:13], 0, v[134:135]
	s_add_i32 m0, s56, 0x2000
	s_nop 0
	global_load_lds_dwordx4 v[142:143], off
	v_lshl_add_u64 v[142:143], v[234:235], 0, s[34:35]
	s_mov_b32 m0, s90
	s_nop 0
	global_load_lds_dwordx4 v[142:143], off
	v_lshl_add_u64 v[142:143], v[244:245], 0, s[34:35]
	s_mov_b32 m0, s97
	s_nop 0
	global_load_lds_dwordx4 v[142:143], off
	s_waitcnt vmcnt(8)
	s_waitcnt lgkmcnt(0)
	s_barrier
	s_setprio 1
	s_waitcnt lgkmcnt(0)
	v_mfma_f32_16x16x32_bf16 v[62:65], v[148:151], v[180:183], v[62:65]
	v_mfma_f32_16x16x32_bf16 v[62:65], v[152:155], v[184:187], v[62:65]
	v_mfma_f32_16x16x32_bf16 v[50:53], v[152:155], v[214:217], v[50:53]
	v_mfma_f32_16x16x32_bf16 v[50:53], v[148:151], v[210:213], v[50:53]
	v_mfma_f32_16x16x32_bf16 v[34:37], v[148:151], v[218:221], v[34:37]
	v_mfma_f32_16x16x32_bf16 v[34:37], v[152:155], v[222:225], v[34:37]
	v_mfma_f32_16x16x32_bf16 v[18:21], v[152:155], v[230:233], v[18:21]
	v_mfma_f32_16x16x32_bf16 v[18:21], v[148:151], v[226:229], v[18:21]
	v_mfma_f32_16x16x32_bf16 v[10:13], v[156:159], v[226:229], v[10:13]
	v_mfma_f32_16x16x32_bf16 v[10:13], v[160:163], v[230:233], v[10:13]
	v_mfma_f32_16x16x32_bf16 v[26:29], v[160:163], v[222:225], v[26:29]
	v_mfma_f32_16x16x32_bf16 v[26:29], v[156:159], v[218:221], v[26:29]
	v_mfma_f32_16x16x32_bf16 v[42:45], v[156:159], v[210:213], v[42:45]
	v_mfma_f32_16x16x32_bf16 v[42:45], v[160:163], v[214:217], v[42:45]
	v_mfma_f32_16x16x32_bf16 v[58:61], v[160:163], v[184:187], v[58:61]
	v_mfma_f32_16x16x32_bf16 v[58:61], v[156:159], v[180:183], v[58:61]
	v_mfma_f32_16x16x32_bf16 v[46:49], v[172:175], v[180:183], v[46:49]
	v_mfma_f32_16x16x32_bf16 v[46:49], v[176:179], v[184:187], v[46:49]
	v_mfma_f32_16x16x32_bf16 v[30:33], v[176:179], v[214:217], v[30:33]
	v_mfma_f32_16x16x32_bf16 v[30:33], v[172:175], v[210:213], v[30:33]
	v_mfma_f32_16x16x32_bf16 v[14:17], v[172:175], v[218:221], v[14:17]
	v_mfma_f32_16x16x32_bf16 v[14:17], v[176:179], v[222:225], v[14:17]
	v_mfma_f32_16x16x32_bf16 v[2:5], v[176:179], v[230:233], v[2:5]
	v_mfma_f32_16x16x32_bf16 v[2:5], v[172:175], v[226:229], v[2:5]
	v_mfma_f32_16x16x32_bf16 v[6:9], v[164:167], v[226:229], v[6:9]
	v_mfma_f32_16x16x32_bf16 v[6:9], v[168:171], v[230:233], v[6:9]
	v_mfma_f32_16x16x32_bf16 v[22:25], v[168:171], v[222:225], v[22:25]
	v_mfma_f32_16x16x32_bf16 v[22:25], v[164:167], v[218:221], v[22:25]
	v_mfma_f32_16x16x32_bf16 v[38:41], v[164:167], v[210:213], v[38:41]
	v_mfma_f32_16x16x32_bf16 v[38:41], v[168:171], v[214:217], v[38:41]
	v_mfma_f32_16x16x32_bf16 v[54:57], v[168:171], v[184:187], v[54:57]
	v_mfma_f32_16x16x32_bf16 v[54:57], v[164:167], v[180:183], v[54:57]
	s_setprio 0
	s_barrier
	s_add_i32 s94, s94, 2
	s_add_u32 s54, s54, 0x100
	s_addc_u32 s55, s55, 0
	s_add_u32 vcc_hi, vcc_hi, 0x100
	s_addc_u32 s61, s61, 0
	s_cmp_gt_u32 s94, 61
	s_cbranch_scc0 .LBB0_252
	s_and_b64 vcc, exec, s[42:43]
	s_cbranch_vccz .LBB0_255
	s_barrier

.LBB0_692:
	s_add_u32 s12, s40, 0xfffc0080
	s_addc_u32 s13, s41, -1
	s_add_i32 s56, 0, 0x10000
	s_cmp_eq_u32 s74, 12
	s_cselect_b32 s63, s47, s13
	s_cselect_b32 s62, s71, s12
	s_cselect_b32 s55, s45, s61
	s_cselect_b32 s54, s72, s73
	s_add_i32 s75, 0, 0x14000
	v_add_u32_e32 v142, s56, v160
	v_add_u32_e32 v163, s75, v160
	ds_read_b128 v[130:133], v142
	ds_read_b128 v[134:137], v142 offset:1024
	ds_read_b128 v[138:141], v142 offset:2048
	ds_read_b128 v[142:145], v142 offset:3072
	ds_read_b128 v[156:159], v163
	ds_read_b128 v[164:167], v163 offset:1024
	ds_read_b128 v[168:171], v163 offset:2048
	ds_read_b128 v[172:175], v163 offset:3072
	v_lshl_add_u64 v[188:189], s[40:41], 0, v[152:153]
	s_add_i32 m0, s53, 0xc000
	ds_read_b128 v[176:179], v162
	ds_read_b128 v[180:183], v162 offset:1024
	ds_read_b128 v[184:187], v162 offset:2048
	ds_read_b128 v[210:213], v162 offset:3072
	ds_read_b128 v[214:217], v162 offset:4096
	ds_read_b128 v[218:221], v162 offset:5120
	ds_read_b128 v[222:225], v162 offset:6144
	ds_read_b128 v[226:229], v162 offset:7168
	global_load_lds_dwordx4 v[188:189], off
	v_lshl_add_u64 v[188:189], s[40:41], 0, v[154:155]
	s_add_i32 m0, s53, 0xe000
	s_nop 0
	global_load_lds_dwordx4 v[188:189], off
	s_waitcnt vmcnt(8)
	s_waitcnt lgkmcnt(0)
	s_barrier
	s_setprio 1
	s_waitcnt lgkmcnt(0)
	v_mfma_f32_16x16x32_bf16 v[126:129], v[130:133], v[176:179], v[126:129]
	v_mfma_f32_16x16x32_bf16 v[126:129], v[134:137], v[180:183], v[126:129]
	v_mfma_f32_16x16x32_bf16 v[114:117], v[134:137], v[210:213], v[114:117]
	v_mfma_f32_16x16x32_bf16 v[114:117], v[130:133], v[184:187], v[114:117]
	v_mfma_f32_16x16x32_bf16 v[98:101], v[130:133], v[214:217], v[98:101]
	v_mfma_f32_16x16x32_bf16 v[98:101], v[134:137], v[218:221], v[98:101]
	v_mfma_f32_16x16x32_bf16 v[82:85], v[134:137], v[226:229], v[82:85]
	v_mfma_f32_16x16x32_bf16 v[82:85], v[130:133], v[222:225], v[82:85]
	v_mfma_f32_16x16x32_bf16 v[74:77], v[138:141], v[222:225], v[74:77]
	v_mfma_f32_16x16x32_bf16 v[74:77], v[142:145], v[226:229], v[74:77]
	v_mfma_f32_16x16x32_bf16 v[90:93], v[142:145], v[218:221], v[90:93]
	v_mfma_f32_16x16x32_bf16 v[90:93], v[138:141], v[214:217], v[90:93]
	v_mfma_f32_16x16x32_bf16 v[106:109], v[138:141], v[184:187], v[106:109]
	v_mfma_f32_16x16x32_bf16 v[106:109], v[142:145], v[210:213], v[106:109]
	v_mfma_f32_16x16x32_bf16 v[122:125], v[142:145], v[180:183], v[122:125]
	v_mfma_f32_16x16x32_bf16 v[122:125], v[138:141], v[176:179], v[122:125]
	v_mfma_f32_16x16x32_bf16 v[110:113], v[168:171], v[176:179], v[110:113]
	v_mfma_f32_16x16x32_bf16 v[110:113], v[172:175], v[180:183], v[110:113]
	v_mfma_f32_16x16x32_bf16 v[94:97], v[172:175], v[210:213], v[94:97]
	v_mfma_f32_16x16x32_bf16 v[94:97], v[168:171], v[184:187], v[94:97]
	v_mfma_f32_16x16x32_bf16 v[78:81], v[168:171], v[214:217], v[78:81]
	v_mfma_f32_16x16x32_bf16 v[78:81], v[172:175], v[218:221], v[78:81]
	v_mfma_f32_16x16x32_bf16 v[66:69], v[172:175], v[226:229], v[66:69]
	v_mfma_f32_16x16x32_bf16 v[66:69], v[168:171], v[222:225], v[66:69]
	v_mfma_f32_16x16x32_bf16 v[70:73], v[156:159], v[222:225], v[70:73]
	v_mfma_f32_16x16x32_bf16 v[70:73], v[164:167], v[226:229], v[70:73]
	v_mfma_f32_16x16x32_bf16 v[86:89], v[164:167], v[218:221], v[86:89]
	v_mfma_f32_16x16x32_bf16 v[86:89], v[156:159], v[214:217], v[86:89]
	v_mfma_f32_16x16x32_bf16 v[102:105], v[156:159], v[184:187], v[102:105]
	v_mfma_f32_16x16x32_bf16 v[102:105], v[164:167], v[210:213], v[102:105]
	v_mfma_f32_16x16x32_bf16 v[118:121], v[164:167], v[180:183], v[118:121]
	v_mfma_f32_16x16x32_bf16 v[118:121], v[156:159], v[176:179], v[118:121]
	s_setprio 0
	s_barrier
	s_add_i32 s12, s56, s59
	v_lshl_add_u64 v[188:189], s[54:55], 0, v[190:191]
	s_mov_b32 m0, s12
	ds_read_b128 v[176:179], v162 offset:16384
	ds_read_b128 v[180:183], v162 offset:17408
	ds_read_b128 v[184:187], v162 offset:18432
	ds_read_b128 v[210:213], v162 offset:19456
	ds_read_b128 v[214:217], v162 offset:20480
	ds_read_b128 v[218:221], v162 offset:21504
	ds_read_b128 v[222:225], v162 offset:22528
	ds_read_b128 v[226:229], v162 offset:23552
	global_load_lds_dwordx4 v[188:189], off
	s_add_i32 m0, s12, 0x2000
	s_add_u32 s12, s54, 0x40000
	v_lshl_add_u64 v[230:231], s[54:55], 0, v[150:151]
	s_addc_u32 s13, s55, 0
	s_add_i32 s56, s75, s59
	global_load_lds_dwordx4 v[230:231], off
	v_lshl_add_u64 v[232:233], s[12:13], 0, v[190:191]
	s_mov_b32 m0, s56
	v_lshl_add_u64 v[234:235], s[62:63], 0, v[148:149]
	global_load_lds_dwordx4 v[232:233], off
	v_lshl_add_u64 v[232:233], s[12:13], 0, v[150:151]
	s_add_i32 m0, s56, 0x2000
	s_nop 0
	global_load_lds_dwordx4 v[232:233], off
	v_lshl_add_u64 v[232:233], s[62:63], 0, v[146:147]
	s_mov_b32 m0, s53
	s_nop 0
	global_load_lds_dwordx4 v[232:233], off
	s_mov_b32 m0, s60
	s_nop 0
	global_load_lds_dwordx4 v[234:235], off
	s_waitcnt vmcnt(8)
	s_waitcnt lgkmcnt(0)
	s_barrier
	s_setprio 1
	s_waitcnt lgkmcnt(0)
	v_mfma_f32_16x16x32_bf16 v[62:65], v[130:133], v[176:179], v[62:65]
	v_mfma_f32_16x16x32_bf16 v[62:65], v[134:137], v[180:183], v[62:65]
	v_mfma_f32_16x16x32_bf16 v[50:53], v[134:137], v[210:213], v[50:53]
	v_mfma_f32_16x16x32_bf16 v[50:53], v[130:133], v[184:187], v[50:53]
	v_mfma_f32_16x16x32_bf16 v[34:37], v[130:133], v[214:217], v[34:37]
	v_mfma_f32_16x16x32_bf16 v[34:37], v[134:137], v[218:221], v[34:37]
	v_mfma_f32_16x16x32_bf16 v[18:21], v[134:137], v[226:229], v[18:21]
	v_mfma_f32_16x16x32_bf16 v[18:21], v[130:133], v[222:225], v[18:21]
	v_mfma_f32_16x16x32_bf16 v[10:13], v[138:141], v[222:225], v[10:13]
	v_mfma_f32_16x16x32_bf16 v[10:13], v[142:145], v[226:229], v[10:13]
	v_mfma_f32_16x16x32_bf16 v[26:29], v[142:145], v[218:221], v[26:29]
	v_mfma_f32_16x16x32_bf16 v[26:29], v[138:141], v[214:217], v[26:29]
	v_mfma_f32_16x16x32_bf16 v[42:45], v[138:141], v[184:187], v[42:45]
	v_mfma_f32_16x16x32_bf16 v[42:45], v[142:145], v[210:213], v[42:45]
	v_mfma_f32_16x16x32_bf16 v[58:61], v[142:145], v[180:183], v[58:61]
	v_mfma_f32_16x16x32_bf16 v[58:61], v[138:141], v[176:179], v[58:61]
	v_mfma_f32_16x16x32_bf16 v[46:49], v[168:171], v[176:179], v[46:49]
	v_mfma_f32_16x16x32_bf16 v[46:49], v[172:175], v[180:183], v[46:49]
	v_mfma_f32_16x16x32_bf16 v[30:33], v[172:175], v[210:213], v[30:33]
	v_mfma_f32_16x16x32_bf16 v[30:33], v[168:171], v[184:187], v[30:33]
	v_mfma_f32_16x16x32_bf16 v[14:17], v[168:171], v[214:217], v[14:17]
	v_mfma_f32_16x16x32_bf16 v[14:17], v[172:175], v[218:221], v[14:17]
	v_mfma_f32_16x16x32_bf16 v[2:5], v[172:175], v[226:229], v[2:5]
	v_mfma_f32_16x16x32_bf16 v[2:5], v[168:171], v[222:225], v[2:5]
	v_mfma_f32_16x16x32_bf16 v[6:9], v[156:159], v[222:225], v[6:9]
	v_mfma_f32_16x16x32_bf16 v[6:9], v[164:167], v[226:229], v[6:9]
	v_mfma_f32_16x16x32_bf16 v[22:25], v[164:167], v[218:221], v[22:25]
	v_mfma_f32_16x16x32_bf16 v[22:25], v[156:159], v[214:217], v[22:25]
	v_mfma_f32_16x16x32_bf16 v[38:41], v[156:159], v[184:187], v[38:41]
	v_mfma_f32_16x16x32_bf16 v[38:41], v[164:167], v[210:213], v[38:41]
	v_mfma_f32_16x16x32_bf16 v[54:57], v[164:167], v[180:183], v[54:57]
	v_mfma_f32_16x16x32_bf16 v[54:57], v[156:159], v[176:179], v[54:57]
	s_setprio 0
	s_barrier
	s_add_i32 s56, 0, 0x18000
	s_add_i32 s75, 0, 0x1c000
	v_add_u32_e32 v142, s56, v160
	v_add_u32_e32 v163, s75, v160
	ds_read_b128 v[130:133], v142
	ds_read_b128 v[134:137], v142 offset:1024
	ds_read_b128 v[138:141], v142 offset:2048
	ds_read_b128 v[142:145], v142 offset:3072
	ds_read_b128 v[156:159], v163
	ds_read_b128 v[164:167], v163 offset:1024
	ds_read_b128 v[168:171], v163 offset:2048
	ds_read_b128 v[172:175], v163 offset:3072
	s_add_u32 s12, s62, 0x40000
	s_addc_u32 s13, s63, 0
	s_mov_b32 m0, s64
	v_lshl_add_u64 v[244:245], s[12:13], 0, v[146:147]
	ds_read_b128 v[176:179], v162 offset:32768
	ds_read_b128 v[180:183], v162 offset:33792
	ds_read_b128 v[184:187], v162 offset:34816
	ds_read_b128 v[210:213], v162 offset:35840
	ds_read_b128 v[214:217], v162 offset:36864
	ds_read_b128 v[218:221], v162 offset:37888
	ds_read_b128 v[222:225], v162 offset:38912
	ds_read_b128 v[226:229], v162 offset:39936
	global_load_lds_dwordx4 v[244:245], off
	v_lshl_add_u64 v[244:245], s[12:13], 0, v[148:149]
	s_mov_b32 m0, s65
	s_nop 0
	global_load_lds_dwordx4 v[244:245], off
	s_waitcnt vmcnt(8)
	s_waitcnt lgkmcnt(0)
	s_barrier
	s_setprio 1
	s_waitcnt lgkmcnt(0)
	v_mfma_f32_16x16x32_bf16 v[126:129], v[130:133], v[176:179], v[126:129]
	v_mfma_f32_16x16x32_bf16 v[126:129], v[134:137], v[180:183], v[126:129]
	v_mfma_f32_16x16x32_bf16 v[114:117], v[134:137], v[210:213], v[114:117]
	v_mfma_f32_16x16x32_bf16 v[114:117], v[130:133], v[184:187], v[114:117]
	v_mfma_f32_16x16x32_bf16 v[98:101], v[130:133], v[214:217], v[98:101]
	v_mfma_f32_16x16x32_bf16 v[98:101], v[134:137], v[218:221], v[98:101]
	v_mfma_f32_16x16x32_bf16 v[82:85], v[134:137], v[226:229], v[82:85]
	v_mfma_f32_16x16x32_bf16 v[82:85], v[130:133], v[222:225], v[82:85]
	v_mfma_f32_16x16x32_bf16 v[74:77], v[138:141], v[222:225], v[74:77]
	v_mfma_f32_16x16x32_bf16 v[74:77], v[142:145], v[226:229], v[74:77]
	v_mfma_f32_16x16x32_bf16 v[90:93], v[142:145], v[218:221], v[90:93]
	v_mfma_f32_16x16x32_bf16 v[90:93], v[138:141], v[214:217], v[90:93]
	v_mfma_f32_16x16x32_bf16 v[106:109], v[138:141], v[184:187], v[106:109]
	v_mfma_f32_16x16x32_bf16 v[106:109], v[142:145], v[210:213], v[106:109]
	v_mfma_f32_16x16x32_bf16 v[122:125], v[142:145], v[180:183], v[122:125]
	v_mfma_f32_16x16x32_bf16 v[122:125], v[138:141], v[176:179], v[122:125]
	v_mfma_f32_16x16x32_bf16 v[110:113], v[168:171], v[176:179], v[110:113]
	v_mfma_f32_16x16x32_bf16 v[110:113], v[172:175], v[180:183], v[110:113]
	v_mfma_f32_16x16x32_bf16 v[94:97], v[172:175], v[210:213], v[94:97]
	v_mfma_f32_16x16x32_bf16 v[94:97], v[168:171], v[184:187], v[94:97]
	v_mfma_f32_16x16x32_bf16 v[78:81], v[168:171], v[214:217], v[78:81]
	v_mfma_f32_16x16x32_bf16 v[78:81], v[172:175], v[218:221], v[78:81]
	v_mfma_f32_16x16x32_bf16 v[66:69], v[172:175], v[226:229], v[66:69]
	v_mfma_f32_16x16x32_bf16 v[66:69], v[168:171], v[222:225], v[66:69]
	v_mfma_f32_16x16x32_bf16 v[70:73], v[156:159], v[222:225], v[70:73]
	v_mfma_f32_16x16x32_bf16 v[70:73], v[164:167], v[226:229], v[70:73]
	v_mfma_f32_16x16x32_bf16 v[86:89], v[164:167], v[218:221], v[86:89]
	v_mfma_f32_16x16x32_bf16 v[86:89], v[156:159], v[214:217], v[86:89]
	v_mfma_f32_16x16x32_bf16 v[102:105], v[156:159], v[184:187], v[102:105]
	v_mfma_f32_16x16x32_bf16 v[102:105], v[164:167], v[210:213], v[102:105]
	v_mfma_f32_16x16x32_bf16 v[118:121], v[164:167], v[180:183], v[118:121]
	v_mfma_f32_16x16x32_bf16 v[118:121], v[156:159], v[176:179], v[118:121]
	s_setprio 0
	s_barrier
	s_add_i32 s12, s56, s59
	v_lshl_add_u64 v[188:189], v[188:189], 0, s[34:35]
	s_mov_b32 m0, s12
	ds_read_b128 v[176:179], v162 offset:49152
	ds_read_b128 v[180:183], v162 offset:50176
	ds_read_b128 v[184:187], v162 offset:51200
	ds_read_b128 v[210:213], v162 offset:52224
	ds_read_b128 v[214:217], v162 offset:53248
	ds_read_b128 v[218:221], v162 offset:54272
	ds_read_b128 v[222:225], v162 offset:55296
	ds_read_b128 v[226:229], v162 offset:56320
	global_load_lds_dwordx4 v[188:189], off
	s_add_i32 m0, s12, 0x2000
	s_add_u32 s12, s54, 0x40080
	v_lshl_add_u64 v[188:189], v[230:231], 0, s[34:35]
	s_addc_u32 s13, s55, 0
	s_add_i32 s54, s75, s59
	global_load_lds_dwordx4 v[188:189], off
	v_lshl_add_u64 v[188:189], s[12:13], 0, v[190:191]
	s_mov_b32 m0, s54
	s_nop 0
	global_load_lds_dwordx4 v[188:189], off
	v_lshl_add_u64 v[188:189], s[12:13], 0, v[150:151]
	s_add_i32 m0, s54, 0x2000
	s_nop 0
	global_load_lds_dwordx4 v[188:189], off
	v_lshl_add_u64 v[188:189], v[232:233], 0, s[34:35]
	s_mov_b32 m0, s66
	s_nop 0
	global_load_lds_dwordx4 v[188:189], off
	v_lshl_add_u64 v[188:189], v[234:235], 0, s[34:35]
	s_mov_b32 m0, s68
	s_nop 0
	global_load_lds_dwordx4 v[188:189], off
	s_waitcnt vmcnt(8)
	s_waitcnt lgkmcnt(0)
	s_barrier
	s_setprio 1
	s_waitcnt lgkmcnt(0)
	v_mfma_f32_16x16x32_bf16 v[62:65], v[130:133], v[176:179], v[62:65]
	v_mfma_f32_16x16x32_bf16 v[62:65], v[134:137], v[180:183], v[62:65]
	v_mfma_f32_16x16x32_bf16 v[50:53], v[134:137], v[210:213], v[50:53]
	v_mfma_f32_16x16x32_bf16 v[50:53], v[130:133], v[184:187], v[50:53]
	v_mfma_f32_16x16x32_bf16 v[34:37], v[130:133], v[214:217], v[34:37]
	v_mfma_f32_16x16x32_bf16 v[34:37], v[134:137], v[218:221], v[34:37]
	v_mfma_f32_16x16x32_bf16 v[18:21], v[134:137], v[226:229], v[18:21]
	v_mfma_f32_16x16x32_bf16 v[18:21], v[130:133], v[222:225], v[18:21]
	v_mfma_f32_16x16x32_bf16 v[10:13], v[138:141], v[222:225], v[10:13]
	v_mfma_f32_16x16x32_bf16 v[10:13], v[142:145], v[226:229], v[10:13]
	v_mfma_f32_16x16x32_bf16 v[26:29], v[142:145], v[218:221], v[26:29]
	v_mfma_f32_16x16x32_bf16 v[26:29], v[138:141], v[214:217], v[26:29]
	v_mfma_f32_16x16x32_bf16 v[42:45], v[138:141], v[184:187], v[42:45]
	v_mfma_f32_16x16x32_bf16 v[42:45], v[142:145], v[210:213], v[42:45]
	v_mfma_f32_16x16x32_bf16 v[58:61], v[142:145], v[180:183], v[58:61]
	v_mfma_f32_16x16x32_bf16 v[58:61], v[138:141], v[176:179], v[58:61]
	v_mfma_f32_16x16x32_bf16 v[46:49], v[168:171], v[176:179], v[46:49]
	v_mfma_f32_16x16x32_bf16 v[46:49], v[172:175], v[180:183], v[46:49]
	v_mfma_f32_16x16x32_bf16 v[30:33], v[172:175], v[210:213], v[30:33]
	v_mfma_f32_16x16x32_bf16 v[30:33], v[168:171], v[184:187], v[30:33]
	v_mfma_f32_16x16x32_bf16 v[14:17], v[168:171], v[214:217], v[14:17]
	v_mfma_f32_16x16x32_bf16 v[14:17], v[172:175], v[218:221], v[14:17]
	v_mfma_f32_16x16x32_bf16 v[2:5], v[172:175], v[226:229], v[2:5]
	v_mfma_f32_16x16x32_bf16 v[2:5], v[168:171], v[222:225], v[2:5]
	v_mfma_f32_16x16x32_bf16 v[6:9], v[156:159], v[222:225], v[6:9]
	v_mfma_f32_16x16x32_bf16 v[6:9], v[164:167], v[226:229], v[6:9]
	v_mfma_f32_16x16x32_bf16 v[22:25], v[164:167], v[218:221], v[22:25]
	v_mfma_f32_16x16x32_bf16 v[22:25], v[156:159], v[214:217], v[22:25]
	v_mfma_f32_16x16x32_bf16 v[38:41], v[156:159], v[184:187], v[38:41]
	v_mfma_f32_16x16x32_bf16 v[38:41], v[164:167], v[210:213], v[38:41]
	v_mfma_f32_16x16x32_bf16 v[54:57], v[164:167], v[180:183], v[54:57]
	v_mfma_f32_16x16x32_bf16 v[54:57], v[156:159], v[176:179], v[54:57]
	s_setprio 0
	s_barrier
	s_add_i32 s74, s74, 2
	s_add_u32 s40, s40, 0x100
	s_addc_u32 s41, s41, 0
	s_add_u32 s73, s73, 0x100
	s_addc_u32 s61, s61, 0
	s_cmp_gt_u32 s74, 13
	s_cbranch_scc0 .LBB0_692
	s_and_b64 vcc, exec, s[30:31]
	s_cbranch_vccz .LBB0_695
	s_barrier

.LBB0_777:
	s_add_u32 s12, s50, 0xfff00080
	s_addc_u32 s13, s51, -1
	s_add_i32 s56, 0, 0x10000
	s_cmp_eq_u32 s72, 60
	s_cselect_b32 s55, s43, s13
	s_cselect_b32 s54, s49, s12
	s_cselect_b32 s53, s41, s61
	s_cselect_b32 s52, s70, s71
	s_add_i32 s73, 0, 0x14000
	v_add_u32_e32 v142, s56, v193
	v_add_u32_e32 v158, s73, v193
	ds_read_b128 v[130:133], v142
	ds_read_b128 v[134:137], v142 offset:1024
	ds_read_b128 v[138:141], v142 offset:2048
	ds_read_b128 v[142:145], v142 offset:3072
	ds_read_b128 v[146:149], v158
	ds_read_b128 v[150:153], v158 offset:1024
	ds_read_b128 v[154:157], v158 offset:2048
	ds_read_b128 v[158:161], v158 offset:3072
	v_lshl_add_u64 v[224:225], s[50:51], 0, v[216:217]
	s_add_i32 m0, s33, 0xc000
	ds_read_b128 v[162:165], v197
	ds_read_b128 v[166:169], v197 offset:1024
	ds_read_b128 v[170:173], v197 offset:2048
	ds_read_b128 v[174:177], v197 offset:3072
	ds_read_b128 v[178:181], v197 offset:4096
	ds_read_b128 v[182:185], v197 offset:5120
	ds_read_b128 v[186:189], v197 offset:6144
	ds_read_b128 v[220:223], v197 offset:7168
	global_load_lds_dwordx4 v[224:225], off
	v_lshl_add_u64 v[224:225], s[50:51], 0, v[218:219]
	s_add_i32 m0, s33, 0xe000
	s_nop 0
	global_load_lds_dwordx4 v[224:225], off
	s_waitcnt vmcnt(8)
	s_waitcnt lgkmcnt(0)
	s_barrier
	s_setprio 1
	s_waitcnt lgkmcnt(0)
	v_mfma_f32_16x16x32_bf16 v[126:129], v[130:133], v[162:165], v[126:129]
	v_mfma_f32_16x16x32_bf16 v[126:129], v[134:137], v[166:169], v[126:129]
	v_mfma_f32_16x16x32_bf16 v[110:113], v[134:137], v[174:177], v[110:113]
	v_mfma_f32_16x16x32_bf16 v[110:113], v[130:133], v[170:173], v[110:113]
	v_mfma_f32_16x16x32_bf16 v[98:101], v[130:133], v[178:181], v[98:101]
	v_mfma_f32_16x16x32_bf16 v[98:101], v[134:137], v[182:185], v[98:101]
	v_mfma_f32_16x16x32_bf16 v[82:85], v[134:137], v[220:223], v[82:85]
	v_mfma_f32_16x16x32_bf16 v[82:85], v[130:133], v[186:189], v[82:85]
	v_mfma_f32_16x16x32_bf16 v[74:77], v[138:141], v[186:189], v[74:77]
	v_mfma_f32_16x16x32_bf16 v[74:77], v[142:145], v[220:223], v[74:77]
	v_mfma_f32_16x16x32_bf16 v[90:93], v[142:145], v[182:185], v[90:93]
	v_mfma_f32_16x16x32_bf16 v[90:93], v[138:141], v[178:181], v[90:93]
	v_mfma_f32_16x16x32_bf16 v[106:109], v[138:141], v[170:173], v[106:109]
	v_mfma_f32_16x16x32_bf16 v[106:109], v[142:145], v[174:177], v[106:109]
	v_mfma_f32_16x16x32_bf16 v[122:125], v[142:145], v[166:169], v[122:125]
	v_mfma_f32_16x16x32_bf16 v[122:125], v[138:141], v[162:165], v[122:125]
	v_mfma_f32_16x16x32_bf16 v[114:117], v[154:157], v[162:165], v[114:117]
	v_mfma_f32_16x16x32_bf16 v[114:117], v[158:161], v[166:169], v[114:117]
	v_mfma_f32_16x16x32_bf16 v[94:97], v[158:161], v[174:177], v[94:97]
	v_mfma_f32_16x16x32_bf16 v[94:97], v[154:157], v[170:173], v[94:97]
	v_mfma_f32_16x16x32_bf16 v[78:81], v[154:157], v[178:181], v[78:81]
	v_mfma_f32_16x16x32_bf16 v[78:81], v[158:161], v[182:185], v[78:81]
	v_mfma_f32_16x16x32_bf16 v[66:69], v[158:161], v[220:223], v[66:69]
	v_mfma_f32_16x16x32_bf16 v[66:69], v[154:157], v[186:189], v[66:69]
	v_mfma_f32_16x16x32_bf16 v[70:73], v[146:149], v[186:189], v[70:73]
	v_mfma_f32_16x16x32_bf16 v[70:73], v[150:153], v[220:223], v[70:73]
	v_mfma_f32_16x16x32_bf16 v[86:89], v[150:153], v[182:185], v[86:89]
	v_mfma_f32_16x16x32_bf16 v[86:89], v[146:149], v[178:181], v[86:89]
	v_mfma_f32_16x16x32_bf16 v[102:105], v[146:149], v[170:173], v[102:105]
	v_mfma_f32_16x16x32_bf16 v[102:105], v[150:153], v[174:177], v[102:105]
	v_mfma_f32_16x16x32_bf16 v[118:121], v[150:153], v[166:169], v[118:121]
	v_mfma_f32_16x16x32_bf16 v[118:121], v[146:149], v[162:165], v[118:121]
	s_setprio 0
	s_barrier
	s_add_i32 s12, s56, s29
	v_lshl_add_u64 v[224:225], s[52:53], 0, v[190:191]
	s_mov_b32 m0, s12
	ds_read_b128 v[162:165], v197 offset:16384
	ds_read_b128 v[166:169], v197 offset:17408
	ds_read_b128 v[170:173], v197 offset:18432
	ds_read_b128 v[174:177], v197 offset:19456
	ds_read_b128 v[178:181], v197 offset:20480
	ds_read_b128 v[182:185], v197 offset:21504
	ds_read_b128 v[186:189], v197 offset:22528
	ds_read_b128 v[220:223], v197 offset:23552
	global_load_lds_dwordx4 v[224:225], off
	s_add_i32 m0, s12, 0x2000
	s_add_u32 s12, s52, 0x100000
	v_lshl_add_u64 v[226:227], s[52:53], 0, v[214:215]
	s_addc_u32 s13, s53, 0
	s_add_i32 s56, s73, s29
	global_load_lds_dwordx4 v[226:227], off
	v_lshl_add_u64 v[228:229], s[12:13], 0, v[190:191]
	s_mov_b32 m0, s56
	v_lshl_add_u64 v[230:231], s[54:55], 0, v[212:213]
	global_load_lds_dwordx4 v[228:229], off
	v_lshl_add_u64 v[228:229], s[12:13], 0, v[214:215]
	s_add_i32 m0, s56, 0x2000
	s_nop 0
	global_load_lds_dwordx4 v[228:229], off
	v_lshl_add_u64 v[228:229], s[54:55], 0, v[210:211]
	s_mov_b32 m0, s33
	s_nop 0
	global_load_lds_dwordx4 v[228:229], off
	s_mov_b32 m0, s62
	s_nop 0
	global_load_lds_dwordx4 v[230:231], off
	s_waitcnt vmcnt(8)
	s_waitcnt lgkmcnt(0)
	s_barrier
	s_setprio 1
	s_waitcnt lgkmcnt(0)
	v_mfma_f32_16x16x32_bf16 v[62:65], v[130:133], v[162:165], v[62:65]
	v_mfma_f32_16x16x32_bf16 v[62:65], v[134:137], v[166:169], v[62:65]
	v_mfma_f32_16x16x32_bf16 v[50:53], v[134:137], v[174:177], v[50:53]
	v_mfma_f32_16x16x32_bf16 v[50:53], v[130:133], v[170:173], v[50:53]
	v_mfma_f32_16x16x32_bf16 v[34:37], v[130:133], v[178:181], v[34:37]
	v_mfma_f32_16x16x32_bf16 v[34:37], v[134:137], v[182:185], v[34:37]
	v_mfma_f32_16x16x32_bf16 v[18:21], v[134:137], v[220:223], v[18:21]
	v_mfma_f32_16x16x32_bf16 v[18:21], v[130:133], v[186:189], v[18:21]
	v_mfma_f32_16x16x32_bf16 v[10:13], v[138:141], v[186:189], v[10:13]
	v_mfma_f32_16x16x32_bf16 v[10:13], v[142:145], v[220:223], v[10:13]
	v_mfma_f32_16x16x32_bf16 v[26:29], v[142:145], v[182:185], v[26:29]
	v_mfma_f32_16x16x32_bf16 v[26:29], v[138:141], v[178:181], v[26:29]
	v_mfma_f32_16x16x32_bf16 v[42:45], v[138:141], v[170:173], v[42:45]
	v_mfma_f32_16x16x32_bf16 v[42:45], v[142:145], v[174:177], v[42:45]
	v_mfma_f32_16x16x32_bf16 v[58:61], v[142:145], v[166:169], v[58:61]
	v_mfma_f32_16x16x32_bf16 v[58:61], v[138:141], v[162:165], v[58:61]
	v_mfma_f32_16x16x32_bf16 v[46:49], v[154:157], v[162:165], v[46:49]
	v_mfma_f32_16x16x32_bf16 v[46:49], v[158:161], v[166:169], v[46:49]
	v_mfma_f32_16x16x32_bf16 v[30:33], v[158:161], v[174:177], v[30:33]
	v_mfma_f32_16x16x32_bf16 v[30:33], v[154:157], v[170:173], v[30:33]
	v_mfma_f32_16x16x32_bf16 v[14:17], v[154:157], v[178:181], v[14:17]
	v_mfma_f32_16x16x32_bf16 v[14:17], v[158:161], v[182:185], v[14:17]
	v_mfma_f32_16x16x32_bf16 v[2:5], v[158:161], v[220:223], v[2:5]
	v_mfma_f32_16x16x32_bf16 v[2:5], v[154:157], v[186:189], v[2:5]
	v_mfma_f32_16x16x32_bf16 v[6:9], v[146:149], v[186:189], v[6:9]
	v_mfma_f32_16x16x32_bf16 v[6:9], v[150:153], v[220:223], v[6:9]
	v_mfma_f32_16x16x32_bf16 v[22:25], v[150:153], v[182:185], v[22:25]
	v_mfma_f32_16x16x32_bf16 v[22:25], v[146:149], v[178:181], v[22:25]
	v_mfma_f32_16x16x32_bf16 v[38:41], v[146:149], v[170:173], v[38:41]
	v_mfma_f32_16x16x32_bf16 v[38:41], v[150:153], v[174:177], v[38:41]
	v_mfma_f32_16x16x32_bf16 v[54:57], v[150:153], v[166:169], v[54:57]
	v_mfma_f32_16x16x32_bf16 v[54:57], v[146:149], v[162:165], v[54:57]
	s_setprio 0
	s_barrier
	s_add_i32 s56, 0, 0x18000
	s_add_i32 s73, 0, 0x1c000
	v_add_u32_e32 v142, s56, v193
	v_add_u32_e32 v158, s73, v193
	ds_read_b128 v[130:133], v142
	ds_read_b128 v[134:137], v142 offset:1024
	ds_read_b128 v[138:141], v142 offset:2048
	ds_read_b128 v[142:145], v142 offset:3072
	ds_read_b128 v[146:149], v158
	ds_read_b128 v[150:153], v158 offset:1024
	ds_read_b128 v[154:157], v158 offset:2048
	ds_read_b128 v[158:161], v158 offset:3072
	s_add_u32 s12, s54, 0x100000
	s_addc_u32 s13, s55, 0
	s_mov_b32 m0, s63
	v_lshl_add_u64 v[232:233], s[12:13], 0, v[210:211]
	ds_read_b128 v[162:165], v197 offset:32768
	ds_read_b128 v[166:169], v197 offset:33792
	ds_read_b128 v[170:173], v197 offset:34816
	ds_read_b128 v[174:177], v197 offset:35840
	ds_read_b128 v[178:181], v197 offset:36864
	ds_read_b128 v[182:185], v197 offset:37888
	ds_read_b128 v[186:189], v197 offset:38912
	ds_read_b128 v[220:223], v197 offset:39936
	global_load_lds_dwordx4 v[232:233], off
	v_lshl_add_u64 v[232:233], s[12:13], 0, v[212:213]
	s_mov_b32 m0, s64
	s_nop 0
	global_load_lds_dwordx4 v[232:233], off
	s_waitcnt vmcnt(8)
	s_waitcnt lgkmcnt(0)
	s_barrier
	s_setprio 1
	s_waitcnt lgkmcnt(0)
	v_mfma_f32_16x16x32_bf16 v[126:129], v[130:133], v[162:165], v[126:129]
	v_mfma_f32_16x16x32_bf16 v[126:129], v[134:137], v[166:169], v[126:129]
	v_mfma_f32_16x16x32_bf16 v[110:113], v[134:137], v[174:177], v[110:113]
	v_mfma_f32_16x16x32_bf16 v[110:113], v[130:133], v[170:173], v[110:113]
	v_mfma_f32_16x16x32_bf16 v[98:101], v[130:133], v[178:181], v[98:101]
	v_mfma_f32_16x16x32_bf16 v[98:101], v[134:137], v[182:185], v[98:101]
	v_mfma_f32_16x16x32_bf16 v[82:85], v[134:137], v[220:223], v[82:85]
	v_mfma_f32_16x16x32_bf16 v[82:85], v[130:133], v[186:189], v[82:85]
	v_mfma_f32_16x16x32_bf16 v[74:77], v[138:141], v[186:189], v[74:77]
	v_mfma_f32_16x16x32_bf16 v[74:77], v[142:145], v[220:223], v[74:77]
	v_mfma_f32_16x16x32_bf16 v[90:93], v[142:145], v[182:185], v[90:93]
	v_mfma_f32_16x16x32_bf16 v[90:93], v[138:141], v[178:181], v[90:93]
	v_mfma_f32_16x16x32_bf16 v[106:109], v[138:141], v[170:173], v[106:109]
	v_mfma_f32_16x16x32_bf16 v[106:109], v[142:145], v[174:177], v[106:109]
	v_mfma_f32_16x16x32_bf16 v[122:125], v[142:145], v[166:169], v[122:125]
	v_mfma_f32_16x16x32_bf16 v[122:125], v[138:141], v[162:165], v[122:125]
	v_mfma_f32_16x16x32_bf16 v[114:117], v[154:157], v[162:165], v[114:117]
	v_mfma_f32_16x16x32_bf16 v[114:117], v[158:161], v[166:169], v[114:117]
	v_mfma_f32_16x16x32_bf16 v[94:97], v[158:161], v[174:177], v[94:97]
	v_mfma_f32_16x16x32_bf16 v[94:97], v[154:157], v[170:173], v[94:97]
	v_mfma_f32_16x16x32_bf16 v[78:81], v[154:157], v[178:181], v[78:81]
	v_mfma_f32_16x16x32_bf16 v[78:81], v[158:161], v[182:185], v[78:81]
	v_mfma_f32_16x16x32_bf16 v[66:69], v[158:161], v[220:223], v[66:69]
	v_mfma_f32_16x16x32_bf16 v[66:69], v[154:157], v[186:189], v[66:69]
	v_mfma_f32_16x16x32_bf16 v[70:73], v[146:149], v[186:189], v[70:73]
	v_mfma_f32_16x16x32_bf16 v[70:73], v[150:153], v[220:223], v[70:73]
	v_mfma_f32_16x16x32_bf16 v[86:89], v[150:153], v[182:185], v[86:89]
	v_mfma_f32_16x16x32_bf16 v[86:89], v[146:149], v[178:181], v[86:89]
	v_mfma_f32_16x16x32_bf16 v[102:105], v[146:149], v[170:173], v[102:105]
	v_mfma_f32_16x16x32_bf16 v[102:105], v[150:153], v[174:177], v[102:105]
	v_mfma_f32_16x16x32_bf16 v[118:121], v[150:153], v[166:169], v[118:121]
	v_mfma_f32_16x16x32_bf16 v[118:121], v[146:149], v[162:165], v[118:121]
	s_setprio 0
	s_barrier
	s_add_i32 s12, s56, s29
	v_lshl_add_u64 v[224:225], v[224:225], 0, s[34:35]
	s_mov_b32 m0, s12
	ds_read_b128 v[162:165], v197 offset:49152
	ds_read_b128 v[166:169], v197 offset:50176
	ds_read_b128 v[170:173], v197 offset:51200
	ds_read_b128 v[174:177], v197 offset:52224
	ds_read_b128 v[178:181], v197 offset:53248
	ds_read_b128 v[182:185], v197 offset:54272
	ds_read_b128 v[186:189], v197 offset:55296
	ds_read_b128 v[220:223], v197 offset:56320
	global_load_lds_dwordx4 v[224:225], off
	s_add_i32 m0, s12, 0x2000
	s_add_u32 s12, s52, 0x100080
	v_lshl_add_u64 v[224:225], v[226:227], 0, s[34:35]
	s_addc_u32 s13, s53, 0
	s_add_i32 s52, s73, s29
	global_load_lds_dwordx4 v[224:225], off
	v_lshl_add_u64 v[224:225], s[12:13], 0, v[190:191]
	s_mov_b32 m0, s52
	s_nop 0
	global_load_lds_dwordx4 v[224:225], off
	v_lshl_add_u64 v[224:225], s[12:13], 0, v[214:215]
	s_add_i32 m0, s52, 0x2000
	s_nop 0
	global_load_lds_dwordx4 v[224:225], off
	v_lshl_add_u64 v[224:225], v[228:229], 0, s[34:35]
	s_mov_b32 m0, s65
	s_nop 0
	global_load_lds_dwordx4 v[224:225], off
	v_lshl_add_u64 v[224:225], v[230:231], 0, s[34:35]
	s_mov_b32 m0, s66
	s_nop 0
	global_load_lds_dwordx4 v[224:225], off
	s_waitcnt vmcnt(8)
	s_waitcnt lgkmcnt(0)
	s_barrier
	s_setprio 1
	s_waitcnt lgkmcnt(0)
	v_mfma_f32_16x16x32_bf16 v[62:65], v[130:133], v[162:165], v[62:65]
	v_mfma_f32_16x16x32_bf16 v[62:65], v[134:137], v[166:169], v[62:65]
	v_mfma_f32_16x16x32_bf16 v[50:53], v[134:137], v[174:177], v[50:53]
	v_mfma_f32_16x16x32_bf16 v[50:53], v[130:133], v[170:173], v[50:53]
	v_mfma_f32_16x16x32_bf16 v[34:37], v[130:133], v[178:181], v[34:37]
	v_mfma_f32_16x16x32_bf16 v[34:37], v[134:137], v[182:185], v[34:37]
	v_mfma_f32_16x16x32_bf16 v[18:21], v[134:137], v[220:223], v[18:21]
	v_mfma_f32_16x16x32_bf16 v[18:21], v[130:133], v[186:189], v[18:21]
	v_mfma_f32_16x16x32_bf16 v[10:13], v[138:141], v[186:189], v[10:13]
	v_mfma_f32_16x16x32_bf16 v[10:13], v[142:145], v[220:223], v[10:13]
	v_mfma_f32_16x16x32_bf16 v[26:29], v[142:145], v[182:185], v[26:29]
	v_mfma_f32_16x16x32_bf16 v[26:29], v[138:141], v[178:181], v[26:29]
	v_mfma_f32_16x16x32_bf16 v[42:45], v[138:141], v[170:173], v[42:45]
	v_mfma_f32_16x16x32_bf16 v[42:45], v[142:145], v[174:177], v[42:45]
	v_mfma_f32_16x16x32_bf16 v[58:61], v[142:145], v[166:169], v[58:61]
	v_mfma_f32_16x16x32_bf16 v[58:61], v[138:141], v[162:165], v[58:61]
	v_mfma_f32_16x16x32_bf16 v[46:49], v[154:157], v[162:165], v[46:49]
	v_mfma_f32_16x16x32_bf16 v[46:49], v[158:161], v[166:169], v[46:49]
	v_mfma_f32_16x16x32_bf16 v[30:33], v[158:161], v[174:177], v[30:33]
	v_mfma_f32_16x16x32_bf16 v[30:33], v[154:157], v[170:173], v[30:33]
	v_mfma_f32_16x16x32_bf16 v[14:17], v[154:157], v[178:181], v[14:17]
	v_mfma_f32_16x16x32_bf16 v[14:17], v[158:161], v[182:185], v[14:17]
	v_mfma_f32_16x16x32_bf16 v[2:5], v[158:161], v[220:223], v[2:5]
	v_mfma_f32_16x16x32_bf16 v[2:5], v[154:157], v[186:189], v[2:5]
	v_mfma_f32_16x16x32_bf16 v[6:9], v[146:149], v[186:189], v[6:9]
	v_mfma_f32_16x16x32_bf16 v[6:9], v[150:153], v[220:223], v[6:9]
	v_mfma_f32_16x16x32_bf16 v[22:25], v[150:153], v[182:185], v[22:25]
	v_mfma_f32_16x16x32_bf16 v[22:25], v[146:149], v[178:181], v[22:25]
	v_mfma_f32_16x16x32_bf16 v[38:41], v[146:149], v[170:173], v[38:41]
	v_mfma_f32_16x16x32_bf16 v[38:41], v[150:153], v[174:177], v[38:41]
	v_mfma_f32_16x16x32_bf16 v[54:57], v[150:153], v[166:169], v[54:57]
	v_mfma_f32_16x16x32_bf16 v[54:57], v[146:149], v[162:165], v[54:57]
	s_setprio 0
	s_barrier
	s_add_i32 s72, s72, 2
	s_add_u32 s50, s50, 0x100
	s_addc_u32 s51, s51, 0
	s_add_u32 s71, s71, 0x100
	s_addc_u32 s61, s61, 0
	s_cmp_gt_u32 s72, 61
	s_cbranch_scc0 .LBB0_777
	s_and_b64 vcc, exec, s[30:31]
	s_cbranch_vccz .LBB0_780
	s_barrier

.LBB0_902:
	s_add_u32 s12, s22, 0xfff00080
	s_addc_u32 s13, s23, -1
	s_add_i32 s56, 0, 0x10000
	s_cmp_eq_u32 s47, 60
	s_cselect_b32 s53, s5, s13
	s_cselect_b32 s52, s10, s12
	v_add_u32_e32 v147, s56, v144
	s_cselect_b32 s31, s25, s45
	s_cselect_b32 s30, s29, s33
	s_add_i32 s61, 0, 0x14000
	ds_read_b128 v[140:143], v147
	ds_read_b128 v[148:151], v147 offset:1024
	ds_read_b128 v[152:155], v147 offset:2048
	ds_read_b128 v[156:159], v147 offset:3072
	v_add_u32_e32 v147, s61, v144
	ds_read_b128 v[160:163], v147
	ds_read_b128 v[164:167], v147 offset:1024
	ds_read_b128 v[168:171], v147 offset:2048
	ds_read_b128 v[172:175], v147 offset:3072
	v_lshl_add_u64 v[188:189], s[22:23], 0, v[136:137]
	s_add_i32 m0, s63, 0xc000
	ds_read_b128 v[176:179], v146
	ds_read_b128 v[180:183], v146 offset:1024
	ds_read_b128 v[184:187], v146 offset:2048
	ds_read_b128 v[210:213], v146 offset:3072
	ds_read_b128 v[214:217], v146 offset:4096
	ds_read_b128 v[218:221], v146 offset:5120
	ds_read_b128 v[222:225], v146 offset:6144
	ds_read_b128 v[226:229], v146 offset:7168
	global_load_lds_dwordx4 v[188:189], off
	v_lshl_add_u64 v[188:189], s[22:23], 0, v[138:139]
	s_add_i32 m0, s63, 0xe000
	s_nop 0
	global_load_lds_dwordx4 v[188:189], off
	s_waitcnt vmcnt(8)
	s_waitcnt lgkmcnt(0)
	s_barrier
	s_setprio 1
	s_waitcnt lgkmcnt(0)
	v_mfma_f32_16x16x32_bf16 v[126:129], v[140:143], v[176:179], v[126:129]
	v_mfma_f32_16x16x32_bf16 v[126:129], v[148:151], v[180:183], v[126:129]
	v_mfma_f32_16x16x32_bf16 v[110:113], v[148:151], v[210:213], v[110:113]
	v_mfma_f32_16x16x32_bf16 v[110:113], v[140:143], v[184:187], v[110:113]
	v_mfma_f32_16x16x32_bf16 v[94:97], v[140:143], v[214:217], v[94:97]
	v_mfma_f32_16x16x32_bf16 v[94:97], v[148:151], v[218:221], v[94:97]
	v_mfma_f32_16x16x32_bf16 v[78:81], v[148:151], v[226:229], v[78:81]
	v_mfma_f32_16x16x32_bf16 v[78:81], v[140:143], v[222:225], v[78:81]
	v_mfma_f32_16x16x32_bf16 v[70:73], v[152:155], v[222:225], v[70:73]
	v_mfma_f32_16x16x32_bf16 v[70:73], v[156:159], v[226:229], v[70:73]
	v_mfma_f32_16x16x32_bf16 v[86:89], v[156:159], v[218:221], v[86:89]
	v_mfma_f32_16x16x32_bf16 v[86:89], v[152:155], v[214:217], v[86:89]
	v_mfma_f32_16x16x32_bf16 v[102:105], v[152:155], v[184:187], v[102:105]
	v_mfma_f32_16x16x32_bf16 v[102:105], v[156:159], v[210:213], v[102:105]
	v_mfma_f32_16x16x32_bf16 v[118:121], v[156:159], v[180:183], v[118:121]
	v_mfma_f32_16x16x32_bf16 v[118:121], v[152:155], v[176:179], v[118:121]
	v_mfma_f32_16x16x32_bf16 v[114:117], v[168:171], v[176:179], v[114:117]
	v_mfma_f32_16x16x32_bf16 v[114:117], v[172:175], v[180:183], v[114:117]
	v_mfma_f32_16x16x32_bf16 v[98:101], v[172:175], v[210:213], v[98:101]
	v_mfma_f32_16x16x32_bf16 v[98:101], v[168:171], v[184:187], v[98:101]
	v_mfma_f32_16x16x32_bf16 v[82:85], v[168:171], v[214:217], v[82:85]
	v_mfma_f32_16x16x32_bf16 v[82:85], v[172:175], v[218:221], v[82:85]
	v_mfma_f32_16x16x32_bf16 v[66:69], v[172:175], v[226:229], v[66:69]
	v_mfma_f32_16x16x32_bf16 v[66:69], v[168:171], v[222:225], v[66:69]
	v_mfma_f32_16x16x32_bf16 v[74:77], v[160:163], v[222:225], v[74:77]
	v_mfma_f32_16x16x32_bf16 v[74:77], v[164:167], v[226:229], v[74:77]
	v_mfma_f32_16x16x32_bf16 v[90:93], v[164:167], v[218:221], v[90:93]
	v_mfma_f32_16x16x32_bf16 v[90:93], v[160:163], v[214:217], v[90:93]
	v_mfma_f32_16x16x32_bf16 v[106:109], v[160:163], v[184:187], v[106:109]
	v_mfma_f32_16x16x32_bf16 v[106:109], v[164:167], v[210:213], v[106:109]
	v_mfma_f32_16x16x32_bf16 v[122:125], v[164:167], v[180:183], v[122:125]
	v_mfma_f32_16x16x32_bf16 v[122:125], v[160:163], v[176:179], v[122:125]
	s_setprio 0
	s_barrier
	s_add_i32 s12, s56, s60
	v_lshl_add_u64 v[188:189], s[30:31], 0, v[190:191]
	s_mov_b32 m0, s12
	ds_read_b128 v[176:179], v146 offset:16384
	ds_read_b128 v[180:183], v146 offset:17408
	ds_read_b128 v[184:187], v146 offset:18432
	ds_read_b128 v[210:213], v146 offset:19456
	ds_read_b128 v[214:217], v146 offset:20480
	ds_read_b128 v[218:221], v146 offset:21504
	ds_read_b128 v[222:225], v146 offset:22528
	ds_read_b128 v[226:229], v146 offset:23552
	global_load_lds_dwordx4 v[188:189], off
	s_add_i32 m0, s12, 0x2000
	s_add_u32 s12, s30, 0x100000
	v_lshl_add_u64 v[230:231], s[30:31], 0, v[130:131]
	s_addc_u32 s13, s31, 0
	s_add_i32 s56, s61, s60
	global_load_lds_dwordx4 v[230:231], off
	v_lshl_add_u64 v[232:233], s[12:13], 0, v[190:191]
	s_mov_b32 m0, s56
	v_lshl_add_u64 v[234:235], s[52:53], 0, v[132:133]
	global_load_lds_dwordx4 v[232:233], off
	v_lshl_add_u64 v[232:233], s[12:13], 0, v[130:131]
	s_add_i32 m0, s56, 0x2000
	s_nop 0
	global_load_lds_dwordx4 v[232:233], off
	v_lshl_add_u64 v[232:233], s[52:53], 0, v[134:135]
	s_mov_b32 m0, s63
	s_nop 0
	global_load_lds_dwordx4 v[232:233], off
	s_mov_b32 m0, s64
	s_nop 0
	global_load_lds_dwordx4 v[234:235], off
	s_waitcnt vmcnt(8)
	s_waitcnt lgkmcnt(0)
	s_barrier
	s_setprio 1
	s_waitcnt lgkmcnt(0)
	v_mfma_f32_16x16x32_bf16 v[62:65], v[140:143], v[176:179], v[62:65]
	v_mfma_f32_16x16x32_bf16 v[62:65], v[148:151], v[180:183], v[62:65]
	v_mfma_f32_16x16x32_bf16 v[46:49], v[148:151], v[210:213], v[46:49]
	v_mfma_f32_16x16x32_bf16 v[46:49], v[140:143], v[184:187], v[46:49]
	v_mfma_f32_16x16x32_bf16 v[30:33], v[140:143], v[214:217], v[30:33]
	v_mfma_f32_16x16x32_bf16 v[30:33], v[148:151], v[218:221], v[30:33]
	v_mfma_f32_16x16x32_bf16 v[14:17], v[148:151], v[226:229], v[14:17]
	v_mfma_f32_16x16x32_bf16 v[14:17], v[140:143], v[222:225], v[14:17]
	v_mfma_f32_16x16x32_bf16 v[6:9], v[152:155], v[222:225], v[6:9]
	v_mfma_f32_16x16x32_bf16 v[6:9], v[156:159], v[226:229], v[6:9]
	v_mfma_f32_16x16x32_bf16 v[22:25], v[156:159], v[218:221], v[22:25]
	v_mfma_f32_16x16x32_bf16 v[22:25], v[152:155], v[214:217], v[22:25]
	v_mfma_f32_16x16x32_bf16 v[38:41], v[152:155], v[184:187], v[38:41]
	v_mfma_f32_16x16x32_bf16 v[38:41], v[156:159], v[210:213], v[38:41]
	v_mfma_f32_16x16x32_bf16 v[54:57], v[156:159], v[180:183], v[54:57]
	v_mfma_f32_16x16x32_bf16 v[54:57], v[152:155], v[176:179], v[54:57]
	v_mfma_f32_16x16x32_bf16 v[50:53], v[168:171], v[176:179], v[50:53]
	v_mfma_f32_16x16x32_bf16 v[50:53], v[172:175], v[180:183], v[50:53]
	v_mfma_f32_16x16x32_bf16 v[34:37], v[172:175], v[210:213], v[34:37]
	v_mfma_f32_16x16x32_bf16 v[34:37], v[168:171], v[184:187], v[34:37]
	v_mfma_f32_16x16x32_bf16 v[18:21], v[168:171], v[214:217], v[18:21]
	v_mfma_f32_16x16x32_bf16 v[18:21], v[172:175], v[218:221], v[18:21]
	v_mfma_f32_16x16x32_bf16 v[2:5], v[172:175], v[226:229], v[2:5]
	v_mfma_f32_16x16x32_bf16 v[2:5], v[168:171], v[222:225], v[2:5]
	v_mfma_f32_16x16x32_bf16 v[10:13], v[160:163], v[222:225], v[10:13]
	v_mfma_f32_16x16x32_bf16 v[10:13], v[164:167], v[226:229], v[10:13]
	v_mfma_f32_16x16x32_bf16 v[26:29], v[164:167], v[218:221], v[26:29]
	v_mfma_f32_16x16x32_bf16 v[26:29], v[160:163], v[214:217], v[26:29]
	v_mfma_f32_16x16x32_bf16 v[42:45], v[160:163], v[184:187], v[42:45]
	v_mfma_f32_16x16x32_bf16 v[42:45], v[164:167], v[210:213], v[42:45]
	v_mfma_f32_16x16x32_bf16 v[58:61], v[164:167], v[180:183], v[58:61]
	v_mfma_f32_16x16x32_bf16 v[58:61], v[160:163], v[176:179], v[58:61]
	s_setprio 0
	s_barrier
	s_add_i32 s56, 0, 0x18000
	v_add_u32_e32 v147, s56, v144
	s_add_i32 s61, 0, 0x1c000
	ds_read_b128 v[140:143], v147
	ds_read_b128 v[148:151], v147 offset:1024
	ds_read_b128 v[152:155], v147 offset:2048
	ds_read_b128 v[156:159], v147 offset:3072
	v_add_u32_e32 v147, s61, v144
	ds_read_b128 v[160:163], v147
	ds_read_b128 v[164:167], v147 offset:1024
	ds_read_b128 v[168:171], v147 offset:2048
	ds_read_b128 v[172:175], v147 offset:3072
	s_add_u32 s12, s52, 0x100000
	s_addc_u32 s13, s53, 0
	s_mov_b32 m0, s65
	v_lshl_add_u64 v[244:245], s[12:13], 0, v[134:135]
	ds_read_b128 v[176:179], v146 offset:32768
	ds_read_b128 v[180:183], v146 offset:33792
	ds_read_b128 v[184:187], v146 offset:34816
	ds_read_b128 v[210:213], v146 offset:35840
	ds_read_b128 v[214:217], v146 offset:36864
	ds_read_b128 v[218:221], v146 offset:37888
	ds_read_b128 v[222:225], v146 offset:38912
	ds_read_b128 v[226:229], v146 offset:39936
	global_load_lds_dwordx4 v[244:245], off
	v_lshl_add_u64 v[244:245], s[12:13], 0, v[132:133]
	s_mov_b32 m0, s66
	s_nop 0
	global_load_lds_dwordx4 v[244:245], off
	s_waitcnt vmcnt(8)
	s_waitcnt lgkmcnt(0)
	s_barrier
	s_setprio 1
	s_waitcnt lgkmcnt(0)
	v_mfma_f32_16x16x32_bf16 v[126:129], v[140:143], v[176:179], v[126:129]
	v_mfma_f32_16x16x32_bf16 v[126:129], v[148:151], v[180:183], v[126:129]
	v_mfma_f32_16x16x32_bf16 v[110:113], v[148:151], v[210:213], v[110:113]
	v_mfma_f32_16x16x32_bf16 v[110:113], v[140:143], v[184:187], v[110:113]
	v_mfma_f32_16x16x32_bf16 v[94:97], v[140:143], v[214:217], v[94:97]
	v_mfma_f32_16x16x32_bf16 v[94:97], v[148:151], v[218:221], v[94:97]
	v_mfma_f32_16x16x32_bf16 v[78:81], v[148:151], v[226:229], v[78:81]
	v_mfma_f32_16x16x32_bf16 v[78:81], v[140:143], v[222:225], v[78:81]
	v_mfma_f32_16x16x32_bf16 v[70:73], v[152:155], v[222:225], v[70:73]
	v_mfma_f32_16x16x32_bf16 v[70:73], v[156:159], v[226:229], v[70:73]
	v_mfma_f32_16x16x32_bf16 v[86:89], v[156:159], v[218:221], v[86:89]
	v_mfma_f32_16x16x32_bf16 v[86:89], v[152:155], v[214:217], v[86:89]
	v_mfma_f32_16x16x32_bf16 v[102:105], v[152:155], v[184:187], v[102:105]
	v_mfma_f32_16x16x32_bf16 v[102:105], v[156:159], v[210:213], v[102:105]
	v_mfma_f32_16x16x32_bf16 v[118:121], v[156:159], v[180:183], v[118:121]
	v_mfma_f32_16x16x32_bf16 v[118:121], v[152:155], v[176:179], v[118:121]
	v_mfma_f32_16x16x32_bf16 v[114:117], v[168:171], v[176:179], v[114:117]
	v_mfma_f32_16x16x32_bf16 v[114:117], v[172:175], v[180:183], v[114:117]
	v_mfma_f32_16x16x32_bf16 v[98:101], v[172:175], v[210:213], v[98:101]
	v_mfma_f32_16x16x32_bf16 v[98:101], v[168:171], v[184:187], v[98:101]
	v_mfma_f32_16x16x32_bf16 v[82:85], v[168:171], v[214:217], v[82:85]
	v_mfma_f32_16x16x32_bf16 v[82:85], v[172:175], v[218:221], v[82:85]
	v_mfma_f32_16x16x32_bf16 v[66:69], v[172:175], v[226:229], v[66:69]
	v_mfma_f32_16x16x32_bf16 v[66:69], v[168:171], v[222:225], v[66:69]
	v_mfma_f32_16x16x32_bf16 v[74:77], v[160:163], v[222:225], v[74:77]
	v_mfma_f32_16x16x32_bf16 v[74:77], v[164:167], v[226:229], v[74:77]
	v_mfma_f32_16x16x32_bf16 v[90:93], v[164:167], v[218:221], v[90:93]
	v_mfma_f32_16x16x32_bf16 v[90:93], v[160:163], v[214:217], v[90:93]
	v_mfma_f32_16x16x32_bf16 v[106:109], v[160:163], v[184:187], v[106:109]
	v_mfma_f32_16x16x32_bf16 v[106:109], v[164:167], v[210:213], v[106:109]
	v_mfma_f32_16x16x32_bf16 v[122:125], v[164:167], v[180:183], v[122:125]
	v_mfma_f32_16x16x32_bf16 v[122:125], v[160:163], v[176:179], v[122:125]
	s_setprio 0
	s_barrier
	s_add_i32 s12, s56, s60
	v_lshl_add_u64 v[188:189], v[188:189], 0, s[34:35]
	s_mov_b32 m0, s12
	ds_read_b128 v[176:179], v146 offset:49152
	ds_read_b128 v[180:183], v146 offset:50176
	ds_read_b128 v[184:187], v146 offset:51200
	ds_read_b128 v[210:213], v146 offset:52224
	ds_read_b128 v[214:217], v146 offset:53248
	ds_read_b128 v[218:221], v146 offset:54272
	ds_read_b128 v[222:225], v146 offset:55296
	ds_read_b128 v[226:229], v146 offset:56320
	global_load_lds_dwordx4 v[188:189], off
	s_add_i32 m0, s12, 0x2000
	s_add_u32 s12, s30, 0x100080
	v_lshl_add_u64 v[188:189], v[230:231], 0, s[34:35]
	s_addc_u32 s13, s31, 0
	s_add_i32 s30, s61, s60
	global_load_lds_dwordx4 v[188:189], off
	v_lshl_add_u64 v[188:189], s[12:13], 0, v[190:191]
	s_mov_b32 m0, s30
	s_nop 0
	global_load_lds_dwordx4 v[188:189], off
	v_lshl_add_u64 v[188:189], s[12:13], 0, v[130:131]
	s_add_i32 m0, s30, 0x2000
	s_nop 0
	global_load_lds_dwordx4 v[188:189], off
	v_lshl_add_u64 v[188:189], v[232:233], 0, s[34:35]
	s_mov_b32 m0, s68
	s_nop 0
	global_load_lds_dwordx4 v[188:189], off
	v_lshl_add_u64 v[188:189], v[234:235], 0, s[34:35]
	s_mov_b32 m0, s69
	s_nop 0
	global_load_lds_dwordx4 v[188:189], off
	s_waitcnt vmcnt(8)
	s_waitcnt lgkmcnt(0)
	s_barrier
	s_setprio 1
	s_waitcnt lgkmcnt(0)
	v_mfma_f32_16x16x32_bf16 v[62:65], v[140:143], v[176:179], v[62:65]
	v_mfma_f32_16x16x32_bf16 v[62:65], v[148:151], v[180:183], v[62:65]
	v_mfma_f32_16x16x32_bf16 v[46:49], v[148:151], v[210:213], v[46:49]
	v_mfma_f32_16x16x32_bf16 v[46:49], v[140:143], v[184:187], v[46:49]
	v_mfma_f32_16x16x32_bf16 v[30:33], v[140:143], v[214:217], v[30:33]
	v_mfma_f32_16x16x32_bf16 v[30:33], v[148:151], v[218:221], v[30:33]
	v_mfma_f32_16x16x32_bf16 v[14:17], v[148:151], v[226:229], v[14:17]
	v_mfma_f32_16x16x32_bf16 v[14:17], v[140:143], v[222:225], v[14:17]
	v_mfma_f32_16x16x32_bf16 v[6:9], v[152:155], v[222:225], v[6:9]
	v_mfma_f32_16x16x32_bf16 v[6:9], v[156:159], v[226:229], v[6:9]
	v_mfma_f32_16x16x32_bf16 v[22:25], v[156:159], v[218:221], v[22:25]
	v_mfma_f32_16x16x32_bf16 v[22:25], v[152:155], v[214:217], v[22:25]
	v_mfma_f32_16x16x32_bf16 v[38:41], v[152:155], v[184:187], v[38:41]
	v_mfma_f32_16x16x32_bf16 v[38:41], v[156:159], v[210:213], v[38:41]
	v_mfma_f32_16x16x32_bf16 v[54:57], v[156:159], v[180:183], v[54:57]
	v_mfma_f32_16x16x32_bf16 v[54:57], v[152:155], v[176:179], v[54:57]
	v_mfma_f32_16x16x32_bf16 v[50:53], v[168:171], v[176:179], v[50:53]
	v_mfma_f32_16x16x32_bf16 v[50:53], v[172:175], v[180:183], v[50:53]
	v_mfma_f32_16x16x32_bf16 v[34:37], v[172:175], v[210:213], v[34:37]
	v_mfma_f32_16x16x32_bf16 v[34:37], v[168:171], v[184:187], v[34:37]
	v_mfma_f32_16x16x32_bf16 v[18:21], v[168:171], v[214:217], v[18:21]
	v_mfma_f32_16x16x32_bf16 v[18:21], v[172:175], v[218:221], v[18:21]
	v_mfma_f32_16x16x32_bf16 v[2:5], v[172:175], v[226:229], v[2:5]
	v_mfma_f32_16x16x32_bf16 v[2:5], v[168:171], v[222:225], v[2:5]
	v_mfma_f32_16x16x32_bf16 v[10:13], v[160:163], v[222:225], v[10:13]
	v_mfma_f32_16x16x32_bf16 v[10:13], v[164:167], v[226:229], v[10:13]
	v_mfma_f32_16x16x32_bf16 v[26:29], v[164:167], v[218:221], v[26:29]
	v_mfma_f32_16x16x32_bf16 v[26:29], v[160:163], v[214:217], v[26:29]
	v_mfma_f32_16x16x32_bf16 v[42:45], v[160:163], v[184:187], v[42:45]
	v_mfma_f32_16x16x32_bf16 v[42:45], v[164:167], v[210:213], v[42:45]
	v_mfma_f32_16x16x32_bf16 v[58:61], v[164:167], v[180:183], v[58:61]
	v_mfma_f32_16x16x32_bf16 v[58:61], v[160:163], v[176:179], v[58:61]
	s_setprio 0
	s_barrier
	s_add_i32 s47, s47, 2
	s_add_u32 s22, s22, 0x100
	s_addc_u32 s23, s23, 0
	s_add_u32 s33, s33, 0x100
	s_addc_u32 s45, s45, 0
	s_cmp_gt_u32 s47, 61
	s_cbranch_scc0 .LBB0_902
	s_and_b64 vcc, exec, s[42:43]
	s_cbranch_vccz .LBB0_905
	s_barrier

.LBB0_983:
	s_add_u32 s46, s44, 0x100
	s_addc_u32 s47, s45, 0
	s_add_i32 s12, 0, 0x10000
	s_cmpk_eq_i32 s70, 0xa8
	s_cselect_b32 s51, s41, s47
	s_cselect_b32 s50, s40, s46
	s_cselect_b32 s49, s43, s69
	s_cselect_b32 s48, s42, s61
	s_add_i32 s56, 0, 0x14000
	v_add_u32_e32 v142, s12, v193
	v_add_u32_e32 v158, s56, v193
	ds_read_b128 v[130:133], v142
	ds_read_b128 v[134:137], v142 offset:1024
	ds_read_b128 v[138:141], v142 offset:2048
	ds_read_b128 v[142:145], v142 offset:3072
	ds_read_b128 v[146:149], v158
	ds_read_b128 v[150:153], v158 offset:1024
	ds_read_b128 v[154:157], v158 offset:2048
	ds_read_b128 v[158:161], v158 offset:3072
	v_lshl_add_u64 v[224:225], s[44:45], 0, v[216:217]
	s_add_i32 m0, s33, 0xc000
	ds_read_b128 v[162:165], v197
	ds_read_b128 v[166:169], v197 offset:1024
	ds_read_b128 v[170:173], v197 offset:2048
	ds_read_b128 v[174:177], v197 offset:3072
	ds_read_b128 v[178:181], v197 offset:4096
	ds_read_b128 v[182:185], v197 offset:5120
	ds_read_b128 v[186:189], v197 offset:6144
	ds_read_b128 v[220:223], v197 offset:7168
	global_load_lds_dwordx4 v[224:225], off
	v_lshl_add_u64 v[224:225], s[44:45], 0, v[218:219]
	s_add_i32 m0, s33, 0xe000
	s_nop 0
	global_load_lds_dwordx4 v[224:225], off
	s_waitcnt vmcnt(8)
	s_waitcnt lgkmcnt(0)
	s_barrier
	s_setprio 1
	s_waitcnt lgkmcnt(0)
	v_mfma_f32_16x16x32_bf16 v[126:129], v[130:133], v[162:165], v[126:129]
	v_mfma_f32_16x16x32_bf16 v[126:129], v[134:137], v[166:169], v[126:129]
	v_mfma_f32_16x16x32_bf16 v[110:113], v[134:137], v[174:177], v[110:113]
	v_mfma_f32_16x16x32_bf16 v[110:113], v[130:133], v[170:173], v[110:113]
	v_mfma_f32_16x16x32_bf16 v[98:101], v[130:133], v[178:181], v[98:101]
	v_mfma_f32_16x16x32_bf16 v[98:101], v[134:137], v[182:185], v[98:101]
	v_mfma_f32_16x16x32_bf16 v[82:85], v[134:137], v[220:223], v[82:85]
	v_mfma_f32_16x16x32_bf16 v[82:85], v[130:133], v[186:189], v[82:85]
	v_mfma_f32_16x16x32_bf16 v[74:77], v[138:141], v[186:189], v[74:77]
	v_mfma_f32_16x16x32_bf16 v[74:77], v[142:145], v[220:223], v[74:77]
	v_mfma_f32_16x16x32_bf16 v[90:93], v[142:145], v[182:185], v[90:93]
	v_mfma_f32_16x16x32_bf16 v[90:93], v[138:141], v[178:181], v[90:93]
	v_mfma_f32_16x16x32_bf16 v[106:109], v[138:141], v[170:173], v[106:109]
	v_mfma_f32_16x16x32_bf16 v[106:109], v[142:145], v[174:177], v[106:109]
	v_mfma_f32_16x16x32_bf16 v[122:125], v[142:145], v[166:169], v[122:125]
	v_mfma_f32_16x16x32_bf16 v[122:125], v[138:141], v[162:165], v[122:125]
	v_mfma_f32_16x16x32_bf16 v[114:117], v[154:157], v[162:165], v[114:117]
	v_mfma_f32_16x16x32_bf16 v[114:117], v[158:161], v[166:169], v[114:117]
	v_mfma_f32_16x16x32_bf16 v[94:97], v[158:161], v[174:177], v[94:97]
	v_mfma_f32_16x16x32_bf16 v[94:97], v[154:157], v[170:173], v[94:97]
	v_mfma_f32_16x16x32_bf16 v[78:81], v[154:157], v[178:181], v[78:81]
	v_mfma_f32_16x16x32_bf16 v[78:81], v[158:161], v[182:185], v[78:81]
	v_mfma_f32_16x16x32_bf16 v[66:69], v[158:161], v[220:223], v[66:69]
	v_mfma_f32_16x16x32_bf16 v[66:69], v[154:157], v[186:189], v[66:69]
	v_mfma_f32_16x16x32_bf16 v[70:73], v[146:149], v[186:189], v[70:73]
	v_mfma_f32_16x16x32_bf16 v[70:73], v[150:153], v[220:223], v[70:73]
	v_mfma_f32_16x16x32_bf16 v[86:89], v[150:153], v[182:185], v[86:89]
	v_mfma_f32_16x16x32_bf16 v[86:89], v[146:149], v[178:181], v[86:89]
	v_mfma_f32_16x16x32_bf16 v[102:105], v[146:149], v[170:173], v[102:105]
	v_mfma_f32_16x16x32_bf16 v[102:105], v[150:153], v[174:177], v[102:105]
	v_mfma_f32_16x16x32_bf16 v[118:121], v[150:153], v[166:169], v[118:121]
	v_mfma_f32_16x16x32_bf16 v[118:121], v[146:149], v[162:165], v[118:121]
	s_setprio 0
	s_barrier
	s_add_i32 s12, s12, s29
	v_lshl_add_u64 v[224:225], s[48:49], 0, v[190:191]
	s_mov_b32 m0, s12
	ds_read_b128 v[162:165], v197 offset:16384
	ds_read_b128 v[166:169], v197 offset:17408
	ds_read_b128 v[170:173], v197 offset:18432
	ds_read_b128 v[174:177], v197 offset:19456
	ds_read_b128 v[178:181], v197 offset:20480
	ds_read_b128 v[182:185], v197 offset:21504
	ds_read_b128 v[186:189], v197 offset:22528
	ds_read_b128 v[220:223], v197 offset:23552
	global_load_lds_dwordx4 v[224:225], off
	s_add_i32 m0, s12, 0x2000
	s_add_u32 s12, s48, 0x2b0000
	v_lshl_add_u64 v[226:227], s[48:49], 0, v[214:215]
	s_addc_u32 s13, s49, 0
	s_add_i32 s44, s56, s29
	global_load_lds_dwordx4 v[226:227], off
	v_lshl_add_u64 v[228:229], s[12:13], 0, v[190:191]
	s_mov_b32 m0, s44
	v_lshl_add_u64 v[230:231], s[50:51], 0, v[212:213]
	global_load_lds_dwordx4 v[228:229], off
	v_lshl_add_u64 v[228:229], s[12:13], 0, v[214:215]
	s_add_i32 m0, s44, 0x2000
	s_nop 0
	global_load_lds_dwordx4 v[228:229], off
	v_lshl_add_u64 v[228:229], s[50:51], 0, v[210:211]
	s_mov_b32 m0, s33
	s_nop 0
	global_load_lds_dwordx4 v[228:229], off
	s_mov_b32 m0, s57
	s_nop 0
	global_load_lds_dwordx4 v[230:231], off
	s_waitcnt vmcnt(8)
	s_waitcnt lgkmcnt(0)
	s_barrier
	s_setprio 1
	s_waitcnt lgkmcnt(0)
	v_mfma_f32_16x16x32_bf16 v[62:65], v[130:133], v[162:165], v[62:65]
	v_mfma_f32_16x16x32_bf16 v[62:65], v[134:137], v[166:169], v[62:65]
	v_mfma_f32_16x16x32_bf16 v[50:53], v[134:137], v[174:177], v[50:53]
	v_mfma_f32_16x16x32_bf16 v[50:53], v[130:133], v[170:173], v[50:53]
	v_mfma_f32_16x16x32_bf16 v[34:37], v[130:133], v[178:181], v[34:37]
	v_mfma_f32_16x16x32_bf16 v[34:37], v[134:137], v[182:185], v[34:37]
	v_mfma_f32_16x16x32_bf16 v[18:21], v[134:137], v[220:223], v[18:21]
	v_mfma_f32_16x16x32_bf16 v[18:21], v[130:133], v[186:189], v[18:21]
	v_mfma_f32_16x16x32_bf16 v[10:13], v[138:141], v[186:189], v[10:13]
	v_mfma_f32_16x16x32_bf16 v[10:13], v[142:145], v[220:223], v[10:13]
	v_mfma_f32_16x16x32_bf16 v[26:29], v[142:145], v[182:185], v[26:29]
	v_mfma_f32_16x16x32_bf16 v[26:29], v[138:141], v[178:181], v[26:29]
	v_mfma_f32_16x16x32_bf16 v[42:45], v[138:141], v[170:173], v[42:45]
	v_mfma_f32_16x16x32_bf16 v[42:45], v[142:145], v[174:177], v[42:45]
	v_mfma_f32_16x16x32_bf16 v[58:61], v[142:145], v[166:169], v[58:61]
	v_mfma_f32_16x16x32_bf16 v[58:61], v[138:141], v[162:165], v[58:61]
	v_mfma_f32_16x16x32_bf16 v[46:49], v[154:157], v[162:165], v[46:49]
	v_mfma_f32_16x16x32_bf16 v[46:49], v[158:161], v[166:169], v[46:49]
	v_mfma_f32_16x16x32_bf16 v[30:33], v[158:161], v[174:177], v[30:33]
	v_mfma_f32_16x16x32_bf16 v[30:33], v[154:157], v[170:173], v[30:33]
	v_mfma_f32_16x16x32_bf16 v[14:17], v[154:157], v[178:181], v[14:17]
	v_mfma_f32_16x16x32_bf16 v[14:17], v[158:161], v[182:185], v[14:17]
	v_mfma_f32_16x16x32_bf16 v[2:5], v[158:161], v[220:223], v[2:5]
	v_mfma_f32_16x16x32_bf16 v[2:5], v[154:157], v[186:189], v[2:5]
	v_mfma_f32_16x16x32_bf16 v[6:9], v[146:149], v[186:189], v[6:9]
	v_mfma_f32_16x16x32_bf16 v[6:9], v[150:153], v[220:223], v[6:9]
	v_mfma_f32_16x16x32_bf16 v[22:25], v[150:153], v[182:185], v[22:25]
	v_mfma_f32_16x16x32_bf16 v[22:25], v[146:149], v[178:181], v[22:25]
	v_mfma_f32_16x16x32_bf16 v[38:41], v[146:149], v[170:173], v[38:41]
	v_mfma_f32_16x16x32_bf16 v[38:41], v[150:153], v[174:177], v[38:41]
	v_mfma_f32_16x16x32_bf16 v[54:57], v[150:153], v[166:169], v[54:57]
	v_mfma_f32_16x16x32_bf16 v[54:57], v[146:149], v[162:165], v[54:57]
	s_setprio 0
	s_barrier
	s_add_i32 s44, 0, 0x18000
	s_add_i32 s45, 0, 0x1c000
	v_add_u32_e32 v142, s44, v193
	v_add_u32_e32 v158, s45, v193
	ds_read_b128 v[130:133], v142
	ds_read_b128 v[134:137], v142 offset:1024
	ds_read_b128 v[138:141], v142 offset:2048
	ds_read_b128 v[142:145], v142 offset:3072
	ds_read_b128 v[146:149], v158
	ds_read_b128 v[150:153], v158 offset:1024
	ds_read_b128 v[154:157], v158 offset:2048
	ds_read_b128 v[158:161], v158 offset:3072
	s_add_u32 s12, s50, 0x2b0000
	s_addc_u32 s13, s51, 0
	s_mov_b32 m0, s58
	v_lshl_add_u64 v[232:233], s[12:13], 0, v[210:211]
	ds_read_b128 v[162:165], v197 offset:32768
	ds_read_b128 v[166:169], v197 offset:33792
	ds_read_b128 v[170:173], v197 offset:34816
	ds_read_b128 v[174:177], v197 offset:35840
	ds_read_b128 v[178:181], v197 offset:36864
	ds_read_b128 v[182:185], v197 offset:37888
	ds_read_b128 v[186:189], v197 offset:38912
	ds_read_b128 v[220:223], v197 offset:39936
	global_load_lds_dwordx4 v[232:233], off
	v_lshl_add_u64 v[232:233], s[12:13], 0, v[212:213]
	s_mov_b32 m0, s59
	s_nop 0
	global_load_lds_dwordx4 v[232:233], off
	s_waitcnt vmcnt(8)
	s_waitcnt lgkmcnt(0)
	s_barrier
	s_setprio 1
	s_waitcnt lgkmcnt(0)
	v_mfma_f32_16x16x32_bf16 v[126:129], v[130:133], v[162:165], v[126:129]
	v_mfma_f32_16x16x32_bf16 v[126:129], v[134:137], v[166:169], v[126:129]
	v_mfma_f32_16x16x32_bf16 v[110:113], v[134:137], v[174:177], v[110:113]
	v_mfma_f32_16x16x32_bf16 v[110:113], v[130:133], v[170:173], v[110:113]
	v_mfma_f32_16x16x32_bf16 v[98:101], v[130:133], v[178:181], v[98:101]
	v_mfma_f32_16x16x32_bf16 v[98:101], v[134:137], v[182:185], v[98:101]
	v_mfma_f32_16x16x32_bf16 v[82:85], v[134:137], v[220:223], v[82:85]
	v_mfma_f32_16x16x32_bf16 v[82:85], v[130:133], v[186:189], v[82:85]
	v_mfma_f32_16x16x32_bf16 v[74:77], v[138:141], v[186:189], v[74:77]
	v_mfma_f32_16x16x32_bf16 v[74:77], v[142:145], v[220:223], v[74:77]
	v_mfma_f32_16x16x32_bf16 v[90:93], v[142:145], v[182:185], v[90:93]
	v_mfma_f32_16x16x32_bf16 v[90:93], v[138:141], v[178:181], v[90:93]
	v_mfma_f32_16x16x32_bf16 v[106:109], v[138:141], v[170:173], v[106:109]
	v_mfma_f32_16x16x32_bf16 v[106:109], v[142:145], v[174:177], v[106:109]
	v_mfma_f32_16x16x32_bf16 v[122:125], v[142:145], v[166:169], v[122:125]
	v_mfma_f32_16x16x32_bf16 v[122:125], v[138:141], v[162:165], v[122:125]
	v_mfma_f32_16x16x32_bf16 v[114:117], v[154:157], v[162:165], v[114:117]
	v_mfma_f32_16x16x32_bf16 v[114:117], v[158:161], v[166:169], v[114:117]
	v_mfma_f32_16x16x32_bf16 v[94:97], v[158:161], v[174:177], v[94:97]
	v_mfma_f32_16x16x32_bf16 v[94:97], v[154:157], v[170:173], v[94:97]
	v_mfma_f32_16x16x32_bf16 v[78:81], v[154:157], v[178:181], v[78:81]
	v_mfma_f32_16x16x32_bf16 v[78:81], v[158:161], v[182:185], v[78:81]
	v_mfma_f32_16x16x32_bf16 v[66:69], v[158:161], v[220:223], v[66:69]
	v_mfma_f32_16x16x32_bf16 v[66:69], v[154:157], v[186:189], v[66:69]
	v_mfma_f32_16x16x32_bf16 v[70:73], v[146:149], v[186:189], v[70:73]
	v_mfma_f32_16x16x32_bf16 v[70:73], v[150:153], v[220:223], v[70:73]
	v_mfma_f32_16x16x32_bf16 v[86:89], v[150:153], v[182:185], v[86:89]
	v_mfma_f32_16x16x32_bf16 v[86:89], v[146:149], v[178:181], v[86:89]
	v_mfma_f32_16x16x32_bf16 v[102:105], v[146:149], v[170:173], v[102:105]
	v_mfma_f32_16x16x32_bf16 v[102:105], v[150:153], v[174:177], v[102:105]
	v_mfma_f32_16x16x32_bf16 v[118:121], v[150:153], v[166:169], v[118:121]
	v_mfma_f32_16x16x32_bf16 v[118:121], v[146:149], v[162:165], v[118:121]
	s_setprio 0
	s_barrier
	s_add_i32 s12, s44, s29
	v_lshl_add_u64 v[224:225], v[224:225], 0, s[34:35]
	s_mov_b32 m0, s12
	ds_read_b128 v[162:165], v197 offset:49152
	ds_read_b128 v[166:169], v197 offset:50176
	ds_read_b128 v[170:173], v197 offset:51200
	ds_read_b128 v[174:177], v197 offset:52224
	ds_read_b128 v[178:181], v197 offset:53248
	ds_read_b128 v[182:185], v197 offset:54272
	ds_read_b128 v[186:189], v197 offset:55296
	ds_read_b128 v[220:223], v197 offset:56320
	global_load_lds_dwordx4 v[224:225], off
	s_add_i32 m0, s12, 0x2000
	s_add_u32 s12, s48, 0x2b0080
	v_lshl_add_u64 v[224:225], v[226:227], 0, s[34:35]
	s_addc_u32 s13, s49, 0
	s_add_i32 s44, s45, s29
	global_load_lds_dwordx4 v[224:225], off
	v_lshl_add_u64 v[224:225], s[12:13], 0, v[190:191]
	s_mov_b32 m0, s44
	s_nop 0
	global_load_lds_dwordx4 v[224:225], off
	v_lshl_add_u64 v[224:225], s[12:13], 0, v[214:215]
	s_add_i32 m0, s44, 0x2000
	s_nop 0
	global_load_lds_dwordx4 v[224:225], off
	v_lshl_add_u64 v[224:225], v[228:229], 0, s[34:35]
	s_mov_b32 m0, s60
	s_nop 0
	global_load_lds_dwordx4 v[224:225], off
	v_lshl_add_u64 v[224:225], v[230:231], 0, s[34:35]
	s_mov_b32 m0, s62
	s_nop 0
	global_load_lds_dwordx4 v[224:225], off
	s_waitcnt vmcnt(8)
	s_waitcnt lgkmcnt(0)
	s_barrier
	s_setprio 1
	s_waitcnt lgkmcnt(0)
	v_mfma_f32_16x16x32_bf16 v[62:65], v[130:133], v[162:165], v[62:65]
	v_mfma_f32_16x16x32_bf16 v[62:65], v[134:137], v[166:169], v[62:65]
	v_mfma_f32_16x16x32_bf16 v[50:53], v[134:137], v[174:177], v[50:53]
	v_mfma_f32_16x16x32_bf16 v[50:53], v[130:133], v[170:173], v[50:53]
	v_mfma_f32_16x16x32_bf16 v[34:37], v[130:133], v[178:181], v[34:37]
	v_mfma_f32_16x16x32_bf16 v[34:37], v[134:137], v[182:185], v[34:37]
	v_mfma_f32_16x16x32_bf16 v[18:21], v[134:137], v[220:223], v[18:21]
	v_mfma_f32_16x16x32_bf16 v[18:21], v[130:133], v[186:189], v[18:21]
	v_mfma_f32_16x16x32_bf16 v[10:13], v[138:141], v[186:189], v[10:13]
	v_mfma_f32_16x16x32_bf16 v[10:13], v[142:145], v[220:223], v[10:13]
	v_mfma_f32_16x16x32_bf16 v[26:29], v[142:145], v[182:185], v[26:29]
	v_mfma_f32_16x16x32_bf16 v[26:29], v[138:141], v[178:181], v[26:29]
	v_mfma_f32_16x16x32_bf16 v[42:45], v[138:141], v[170:173], v[42:45]
	v_mfma_f32_16x16x32_bf16 v[42:45], v[142:145], v[174:177], v[42:45]
	v_mfma_f32_16x16x32_bf16 v[58:61], v[142:145], v[166:169], v[58:61]
	v_mfma_f32_16x16x32_bf16 v[58:61], v[138:141], v[162:165], v[58:61]
	v_mfma_f32_16x16x32_bf16 v[46:49], v[154:157], v[162:165], v[46:49]
	v_mfma_f32_16x16x32_bf16 v[46:49], v[158:161], v[166:169], v[46:49]
	v_mfma_f32_16x16x32_bf16 v[30:33], v[158:161], v[174:177], v[30:33]
	v_mfma_f32_16x16x32_bf16 v[30:33], v[154:157], v[170:173], v[30:33]
	v_mfma_f32_16x16x32_bf16 v[14:17], v[154:157], v[178:181], v[14:17]
	v_mfma_f32_16x16x32_bf16 v[14:17], v[158:161], v[182:185], v[14:17]
	v_mfma_f32_16x16x32_bf16 v[2:5], v[158:161], v[220:223], v[2:5]
	v_mfma_f32_16x16x32_bf16 v[2:5], v[154:157], v[186:189], v[2:5]
	v_mfma_f32_16x16x32_bf16 v[6:9], v[146:149], v[186:189], v[6:9]
	v_mfma_f32_16x16x32_bf16 v[6:9], v[150:153], v[220:223], v[6:9]
	v_mfma_f32_16x16x32_bf16 v[22:25], v[150:153], v[182:185], v[22:25]
	v_mfma_f32_16x16x32_bf16 v[22:25], v[146:149], v[178:181], v[22:25]
	v_mfma_f32_16x16x32_bf16 v[38:41], v[146:149], v[170:173], v[38:41]
	v_mfma_f32_16x16x32_bf16 v[38:41], v[150:153], v[174:177], v[38:41]
	v_mfma_f32_16x16x32_bf16 v[54:57], v[150:153], v[166:169], v[54:57]
	v_mfma_f32_16x16x32_bf16 v[54:57], v[146:149], v[162:165], v[54:57]
	s_setprio 0
	s_barrier
	s_add_i32 s70, s70, 2
	s_add_u32 s61, s61, 0x100
	s_addc_u32 s69, s69, 0
	s_cmpk_gt_u32 s70, 0xa9
	s_mov_b64 s[44:45], s[46:47]
	s_cbranch_scc0 .LBB0_983
	s_and_b64 vcc, exec, s[30:31]
	s_cbranch_vccz .LBB0_986
	s_barrier
